# intra-SIMD wave stagger in attention units: waves 4-7 sleep before QK (xattn 32, DIL 10) and before PV (4, 3)
# baseline (speedup 1.0000x reference)
; #define LAS __attribute__((address_space(3)))
; __device__ __forceinline__ void glds16(const void* gsrc, LAS unsigned char* dst_uniform) { __builtin_amdgcn_global_load_lds((const unsigned*)gsrc, (LAS unsigned*)dst_uniform, 16, 0, 0); }
; #define ATT_SYNC() do { asm volatile("s_waitcnt vmcnt(0) lgkmcnt(0)" ::: "memory"); __syncthreads(); } while (0)
; __device__ __forceinline__ void xattn_unit(LAS unsigned char* lds, const bf16_t* Qx, const bf16_t* KV, int li, int b, int h, int qb, bf16_t* XO, const int tid) {
;     ...
;     for (int ii = 0; ii < 16; ++ii) { const int i = wid * 16 + ii, key = 2 * i + hi, c = r32 ^ (key & 15);
;         glds16(Kb + (size_t)key * 8192 + c * 8, lds + i * 1024); }
;     bf16x8 qf[16]; { const bf16_t* qp = Qx + tok * 1024 + h * 256 + hi * 8;
; #pragma unroll
;         for (int s = 0; s < 16; ++s) qf[s] = *(const bf16x8*)(qp + 16 * s); }
;     ATT_SYNC();
;     f32x16 S[8];
; #pragma unroll
;     for (int kt = 0; kt < 8; ++kt) { f32x16 acc = {}; const lds_cptr kp = (lds_cptr)lds + (32 * kt + r32) * 512;
; #pragma unroll
;         for (int s = 0; s < 16; ++s) { const bf16x8 kf = *(const LAS bf16x8*)(kp + (((2 * s + hi) ^ (r32 & 15)) << 4)); acc = __builtin_amdgcn_mfma_f32_32x32x16_bf16(kf, qf[s], acc, 0, 0, 0); }
.LBB0_432:
	v_add_u32_e32 v1, -6, v0
	v_bitop3_b32 v1, v1, v203, 9 bitop3:0x6c
	v_lshlrev_b32_e32 v208, 4, v1
	v_lshl_add_u64 v[10:11], v[8:9], 0, s[18:19]
	s_add_i32 s26, s24, s25
	v_add_u32_e32 v1, -4, v0
	v_lshl_add_u64 v[10:11], v[10:11], 0, v[208:209]
	s_mov_b32 m0, s26
	v_bitop3_b32 v1, v1, v203, 11 bitop3:0x6c
	global_load_lds_dwordx4 v[10:11], off
	v_lshlrev_b32_e32 v208, 4, v1
	v_lshl_add_u64 v[10:11], v[6:7], 0, s[18:19]
	v_add_u32_e32 v1, -2, v0
	v_lshl_add_u64 v[10:11], v[10:11], 0, v[208:209]
	s_add_i32 m0, s26, 0x400
	v_bitop3_b32 v1, v1, v203, 13 bitop3:0x6c
	global_load_lds_dwordx4 v[10:11], off
	v_lshlrev_b32_e32 v208, 4, v1
	v_lshl_add_u64 v[10:11], v[4:5], 0, s[18:19]
	v_lshl_add_u64 v[10:11], v[10:11], 0, v[208:209]
	s_add_i32 m0, s26, 0x800
	v_bitop3_b32 v1, v0, v203, 15 bitop3:0x6c
	global_load_lds_dwordx4 v[10:11], off
	v_lshlrev_b32_e32 v208, 4, v1
	v_lshl_add_u64 v[10:11], v[2:3], 0, s[18:19]
	v_lshl_add_u64 v[10:11], v[10:11], 0, v[208:209]
	s_add_i32 m0, s26, 0xc00
	s_addk_i32 s25, 0x1000
	global_load_lds_dwordx4 v[10:11], off
	v_lshl_add_u64 v[2:3], v[2:3], 0, s[28:29]
	v_add_u32_e32 v0, 8, v0
	v_lshl_add_u64 v[4:5], v[4:5], 0, s[28:29]
	v_lshl_add_u64 v[6:7], v[6:7], 0, s[28:29]
	v_lshl_add_u64 v[8:9], v[8:9], 0, s[28:29]
	s_cmpk_eq_i32 s25, 0x4000
	s_cbranch_scc0 .LBB0_432
	s_lshl_b32 s25, s30, 8
	s_and_b32 s25, s25, 0xf00
	s_lshl_b64 s[0:1], s[0:1], 12
	v_or_b32_e32 v0, s25, v203
	s_ashr_i32 s37, s36, 31
	v_or_b32_e32 v0, s0, v0
	v_mov_b32_e32 v1, s1
	v_lshl_add_u64 v[0:1], v[0:1], 0, s[36:37]
	v_lshlrev_b64 v[200:201], 10, v[0:1]
	v_lshlrev_b64 v[0:1], 11, v[0:1]
	v_lshl_add_u64 v[0:1], s[8:9], 0, v[0:1]
	v_lshl_add_u64 v[0:1], s[12:13], 1, v[0:1]
	v_mov_b32_e32 v197, v209
	v_lshl_add_u64 v[0:1], v[0:1], 0, v[196:197]
	global_load_dwordx4 v[112:115], v[0:1], off
	global_load_dwordx4 v[184:187], v[0:1], off offset:32
	global_load_dwordx4 v[180:183], v[0:1], off offset:64
	global_load_dwordx4 v[176:179], v[0:1], off offset:96
	global_load_dwordx4 v[172:175], v[0:1], off offset:128
	global_load_dwordx4 v[168:171], v[0:1], off offset:160
	global_load_dwordx4 v[164:167], v[0:1], off offset:192
	global_load_dwordx4 v[160:163], v[0:1], off offset:224
	global_load_dwordx4 v[156:159], v[0:1], off offset:256
	global_load_dwordx4 v[152:155], v[0:1], off offset:288
	global_load_dwordx4 v[148:151], v[0:1], off offset:320
	global_load_dwordx4 v[144:147], v[0:1], off offset:352
	global_load_dwordx4 v[140:143], v[0:1], off offset:384
	global_load_dwordx4 v[136:139], v[0:1], off offset:416
	global_load_dwordx4 v[132:135], v[0:1], off offset:448
	global_load_dwordx4 v[128:131], v[0:1], off offset:480
	v_add_u32_e32 v32, v205, v206
	s_waitcnt vmcnt(0) lgkmcnt(0)
	s_waitcnt vmcnt(0) lgkmcnt(0)
	s_barrier
	v_readfirstlane_b32 s98, v202
	s_nop 3
	s_bitcmp1_b32 s98, 8
	s_cbranch_scc0 .Lxa_stag1
	s_sleep 32
.Lxa_stag1:
	ds_read_b128 v[0:3], v32
	v_add_u32_e32 v78, v205, v207
	ds_read_b128 v[16:19], v78
	v_add_u32_e32 v77, v205, v211
	v_add_u32_e32 v76, v205, v212
	v_add_u32_e32 v75, v205, v218
	v_add_u32_e32 v74, v205, v219
	v_add_u32_e32 v73, v205, v220
	v_add_u32_e32 v72, v205, v221
	v_add_u32_e32 v71, v205, v237
	v_add_u32_e32 v70, v205, v238
	v_add_u32_e32 v69, v205, v239
	v_add_u32_e32 v68, v205, v240
	v_add_u32_e32 v67, v205, v241
	v_add_u32_e32 v66, v205, v242
	v_add_u32_e32 v65, v205, v243
	v_add_u32_e32 v64, v205, v244
	v_add_u32_e32 v197, v248, v207
	v_add_u32_e32 v96, v246, v207
	v_add_u32_e32 v116, v247, v207
	s_add_u32 s14, s14, s18
	s_addc_u32 s15, s15, s19
	s_lshl_b64 s[0:1], s[36:37], 1
	s_add_u32 s0, s14, s0
	s_addc_u32 s1, s15, s1
	s_waitcnt lgkmcnt(1)
	v_mfma_f32_32x32x16_bf16 v[0:15], v[0:3], v[112:115], 0
	ds_read_b128 v[222:225], v197
	ds_read_b128 v[34:37], v78 offset:16384
	ds_read_b128 v[96:99], v96
	ds_read_b128 v[116:119], v116
	s_waitcnt lgkmcnt(4)
	v_mfma_f32_32x32x16_bf16 v[0:15], v[16:19], v[184:187], v[0:15]
	ds_read_b128 v[16:19], v77
	s_waitcnt lgkmcnt(0)
	v_mfma_f32_32x32x16_bf16 v[0:15], v[16:19], v[180:183], v[0:15]
	ds_read_b128 v[16:19], v76
	s_waitcnt lgkmcnt(0)
	v_mfma_f32_32x32x16_bf16 v[0:15], v[16:19], v[176:179], v[0:15]
	ds_read_b128 v[16:19], v75
	s_waitcnt lgkmcnt(0)
	v_mfma_f32_32x32x16_bf16 v[0:15], v[16:19], v[172:175], v[0:15]
	ds_read_b128 v[16:19], v74
	s_waitcnt lgkmcnt(0)
	v_mfma_f32_32x32x16_bf16 v[0:15], v[16:19], v[168:171], v[0:15]
	ds_read_b128 v[16:19], v73
	s_waitcnt lgkmcnt(0)
	v_mfma_f32_32x32x16_bf16 v[0:15], v[16:19], v[164:167], v[0:15]
	ds_read_b128 v[16:19], v72
	s_waitcnt lgkmcnt(0)
	v_mfma_f32_32x32x16_bf16 v[0:15], v[16:19], v[160:163], v[0:15]
	ds_read_b128 v[16:19], v71
	s_waitcnt lgkmcnt(0)
	v_mfma_f32_32x32x16_bf16 v[0:15], v[16:19], v[156:159], v[0:15]
	ds_read_b128 v[16:19], v70
	s_waitcnt lgkmcnt(0)
	v_mfma_f32_32x32x16_bf16 v[0:15], v[16:19], v[152:155], v[0:15]
	ds_read_b128 v[16:19], v69
	s_waitcnt lgkmcnt(0)
	v_mfma_f32_32x32x16_bf16 v[0:15], v[16:19], v[148:151], v[0:15]
	ds_read_b128 v[16:19], v68
	s_waitcnt lgkmcnt(0)
	v_mfma_f32_32x32x16_bf16 v[0:15], v[16:19], v[144:147], v[0:15]
	ds_read_b128 v[16:19], v67
	s_waitcnt lgkmcnt(0)
	v_mfma_f32_32x32x16_bf16 v[0:15], v[16:19], v[140:143], v[0:15]
	ds_read_b128 v[16:19], v66
	s_waitcnt lgkmcnt(0)
	v_mfma_f32_32x32x16_bf16 v[0:15], v[16:19], v[136:139], v[0:15]
	ds_read_b128 v[16:19], v65
	s_waitcnt lgkmcnt(0)
	v_mfma_f32_32x32x16_bf16 v[0:15], v[16:19], v[132:135], v[0:15]
	ds_read_b128 v[16:19], v64
	s_waitcnt lgkmcnt(0)
	v_mfma_f32_32x32x16_bf16 v[0:15], v[16:19], v[128:131], v[0:15]
	ds_read_b128 v[16:19], v32 offset:16384
	s_waitcnt lgkmcnt(0)
; #define LAS __attribute__((address_space(3)))
; __device__ __forceinline__ void xattn_unit(LAS unsigned char* lds, const bf16_t* Qx, const bf16_t* KV, int li, int b, int h, int qb, bf16_t* XO, const int tid) {
;     ...
;     for (int kt = 0; kt < 8; ++kt) { f32x16 acc = {}; const lds_cptr kp = (lds_cptr)lds + (32 * kt + r32) * 512;
; #pragma unroll
;         for (int s = 0; s < 16; ++s) { const bf16x8 kf = *(const LAS bf16x8*)(kp + (((2 * s + hi) ^ (r32 & 15)) << 4)); acc = __builtin_amdgcn_mfma_f32_32x32x16_bf16(kf, qf[s], acc, 0, 0, 0); }
;         S[kt] = acc; }
	v_mfma_f32_32x32x16_bf16 v[16:31], v[16:19], v[112:115], 0
	v_mfma_f32_32x32x16_bf16 v[16:31], v[34:37], v[184:187], v[16:31]
	ds_read_b128 v[34:37], v77 offset:16384
	s_waitcnt lgkmcnt(0)
	v_mfma_f32_32x32x16_bf16 v[16:31], v[34:37], v[180:183], v[16:31]
	ds_read_b128 v[34:37], v76 offset:16384
	s_waitcnt lgkmcnt(0)
	v_mfma_f32_32x32x16_bf16 v[16:31], v[34:37], v[176:179], v[16:31]
	ds_read_b128 v[34:37], v75 offset:16384
	s_waitcnt lgkmcnt(0)
	v_mfma_f32_32x32x16_bf16 v[16:31], v[34:37], v[172:175], v[16:31]
	ds_read_b128 v[34:37], v74 offset:16384
	s_waitcnt lgkmcnt(0)
	v_mfma_f32_32x32x16_bf16 v[16:31], v[34:37], v[168:171], v[16:31]
	ds_read_b128 v[34:37], v73 offset:16384
	s_waitcnt lgkmcnt(0)
	v_mfma_f32_32x32x16_bf16 v[16:31], v[34:37], v[164:167], v[16:31]
	ds_read_b128 v[34:37], v72 offset:16384
	s_waitcnt lgkmcnt(0)
	v_mfma_f32_32x32x16_bf16 v[16:31], v[34:37], v[160:163], v[16:31]
	ds_read_b128 v[34:37], v71 offset:16384
	s_waitcnt lgkmcnt(0)
	v_mfma_f32_32x32x16_bf16 v[16:31], v[34:37], v[156:159], v[16:31]
	ds_read_b128 v[34:37], v70 offset:16384
	s_waitcnt lgkmcnt(0)
	v_mfma_f32_32x32x16_bf16 v[16:31], v[34:37], v[152:155], v[16:31]
	ds_read_b128 v[34:37], v69 offset:16384
	s_waitcnt lgkmcnt(0)
	v_mfma_f32_32x32x16_bf16 v[16:31], v[34:37], v[148:151], v[16:31]
	ds_read_b128 v[34:37], v68 offset:16384
	s_waitcnt lgkmcnt(0)
	v_mfma_f32_32x32x16_bf16 v[16:31], v[34:37], v[144:147], v[16:31]
	ds_read_b128 v[34:37], v67 offset:16384
	s_waitcnt lgkmcnt(0)
	v_mfma_f32_32x32x16_bf16 v[16:31], v[34:37], v[140:143], v[16:31]
	ds_read_b128 v[34:37], v66 offset:16384
	s_waitcnt lgkmcnt(0)
	v_mfma_f32_32x32x16_bf16 v[16:31], v[34:37], v[136:139], v[16:31]
	ds_read_b128 v[34:37], v65 offset:16384
	s_waitcnt lgkmcnt(0)
	v_mfma_f32_32x32x16_bf16 v[16:31], v[34:37], v[132:135], v[16:31]
	ds_read_b128 v[34:37], v64 offset:16384
	s_waitcnt lgkmcnt(0)
	v_mfma_f32_32x32x16_bf16 v[16:31], v[34:37], v[128:131], v[16:31]
	ds_read_b128 v[34:37], v32 offset:32768
	s_waitcnt lgkmcnt(0)
	v_mfma_f32_32x32x16_bf16 v[48:63], v[34:37], v[112:115], 0
	ds_read_b128 v[34:37], v78 offset:32768
	ds_read_b128 v[78:81], v78 offset:49152
	s_waitcnt lgkmcnt(1)
	v_mfma_f32_32x32x16_bf16 v[48:63], v[34:37], v[184:187], v[48:63]
	ds_read_b128 v[34:37], v77 offset:32768
	s_waitcnt lgkmcnt(0)
	v_mfma_f32_32x32x16_bf16 v[48:63], v[34:37], v[180:183], v[48:63]
	ds_read_b128 v[34:37], v76 offset:32768
	s_waitcnt lgkmcnt(0)
	v_mfma_f32_32x32x16_bf16 v[48:63], v[34:37], v[176:179], v[48:63]
	ds_read_b128 v[34:37], v75 offset:32768
	s_waitcnt lgkmcnt(0)
	v_mfma_f32_32x32x16_bf16 v[48:63], v[34:37], v[172:175], v[48:63]
	ds_read_b128 v[34:37], v74 offset:32768
	s_waitcnt lgkmcnt(0)
	v_mfma_f32_32x32x16_bf16 v[48:63], v[34:37], v[168:171], v[48:63]
	ds_read_b128 v[34:37], v73 offset:32768
	s_waitcnt lgkmcnt(0)
	v_mfma_f32_32x32x16_bf16 v[48:63], v[34:37], v[164:167], v[48:63]
	ds_read_b128 v[34:37], v72 offset:32768
	s_waitcnt lgkmcnt(0)
	v_mfma_f32_32x32x16_bf16 v[48:63], v[34:37], v[160:163], v[48:63]
	ds_read_b128 v[34:37], v71 offset:32768
	s_waitcnt lgkmcnt(0)
	v_mfma_f32_32x32x16_bf16 v[48:63], v[34:37], v[156:159], v[48:63]
	ds_read_b128 v[34:37], v70 offset:32768
	s_waitcnt lgkmcnt(0)
	v_mfma_f32_32x32x16_bf16 v[48:63], v[34:37], v[152:155], v[48:63]
	ds_read_b128 v[34:37], v69 offset:32768
	s_waitcnt lgkmcnt(0)
	v_mfma_f32_32x32x16_bf16 v[48:63], v[34:37], v[148:151], v[48:63]
	ds_read_b128 v[34:37], v68 offset:32768
	s_waitcnt lgkmcnt(0)
	v_mfma_f32_32x32x16_bf16 v[48:63], v[34:37], v[144:147], v[48:63]
	ds_read_b128 v[34:37], v67 offset:32768
	s_waitcnt lgkmcnt(0)
	v_mfma_f32_32x32x16_bf16 v[48:63], v[34:37], v[140:143], v[48:63]
	ds_read_b128 v[34:37], v66 offset:32768
	s_waitcnt lgkmcnt(0)
	v_mfma_f32_32x32x16_bf16 v[48:63], v[34:37], v[136:139], v[48:63]
	ds_read_b128 v[34:37], v65 offset:32768
	s_waitcnt lgkmcnt(0)
	v_mfma_f32_32x32x16_bf16 v[48:63], v[34:37], v[132:135], v[48:63]
	ds_read_b128 v[34:37], v64 offset:32768
	s_waitcnt lgkmcnt(0)
	v_mfma_f32_32x32x16_bf16 v[48:63], v[34:37], v[128:131], v[48:63]
	ds_read_b128 v[32:35], v32 offset:49152
	s_waitcnt lgkmcnt(0)
	v_mfma_f32_32x32x16_bf16 v[32:47], v[32:35], v[112:115], 0
	v_mfma_f32_32x32x16_bf16 v[32:47], v[78:81], v[184:187], v[32:47]
	ds_read_b128 v[78:81], v77 offset:49152
	s_waitcnt lgkmcnt(0)
	v_mfma_f32_32x32x16_bf16 v[32:47], v[78:81], v[180:183], v[32:47]
	ds_read_b128 v[76:79], v76 offset:49152
	v_add_u32_e32 v80, v245, v207
	ds_read_b128 v[80:83], v80
	s_waitcnt lgkmcnt(1)
	v_mfma_f32_32x32x16_bf16 v[32:47], v[76:79], v[176:179], v[32:47]
	ds_read_b128 v[76:79], v75 offset:49152
	s_waitcnt lgkmcnt(0)
	v_mfma_f32_32x32x16_bf16 v[32:47], v[76:79], v[172:175], v[32:47]
	ds_read_b128 v[74:77], v74 offset:49152
	s_waitcnt lgkmcnt(0)
	v_mfma_f32_32x32x16_bf16 v[32:47], v[74:77], v[168:171], v[32:47]
	ds_read_b128 v[74:77], v73 offset:49152
	s_waitcnt lgkmcnt(0)
	v_mfma_f32_32x32x16_bf16 v[32:47], v[74:77], v[164:167], v[32:47]
	ds_read_b128 v[72:75], v72 offset:49152
	s_waitcnt lgkmcnt(0)
	v_mfma_f32_32x32x16_bf16 v[32:47], v[72:75], v[160:163], v[32:47]
	ds_read_b128 v[72:75], v71 offset:49152
	s_waitcnt lgkmcnt(0)
	v_mfma_f32_32x32x16_bf16 v[32:47], v[72:75], v[156:159], v[32:47]
	ds_read_b128 v[70:73], v70 offset:49152
	s_waitcnt lgkmcnt(0)
	v_mfma_f32_32x32x16_bf16 v[32:47], v[70:73], v[152:155], v[32:47]
	ds_read_b128 v[70:73], v69 offset:49152
	s_waitcnt lgkmcnt(0)
	v_mfma_f32_32x32x16_bf16 v[32:47], v[70:73], v[148:151], v[32:47]
	ds_read_b128 v[68:71], v68 offset:49152
	s_waitcnt lgkmcnt(0)
	v_mfma_f32_32x32x16_bf16 v[32:47], v[68:71], v[144:147], v[32:47]
	ds_read_b128 v[68:71], v67 offset:49152
	s_waitcnt lgkmcnt(0)
; #define LAS __attribute__((address_space(3)))
; __device__ __forceinline__ void xattn_unit(LAS unsigned char* lds, const bf16_t* Qx, const bf16_t* KV, int li, int b, int h, int qb, bf16_t* XO, const int tid) {
;     ...
;     for (int kt = 0; kt < 8; ++kt) { f32x16 acc = {}; const lds_cptr kp = (lds_cptr)lds + (32 * kt + r32) * 512;
; #pragma unroll
;         for (int s = 0; s < 16; ++s) { const bf16x8 kf = *(const LAS bf16x8*)(kp + (((2 * s + hi) ^ (r32 & 15)) << 4)); acc = __builtin_amdgcn_mfma_f32_32x32x16_bf16(kf, qf[s], acc, 0, 0, 0); }
;         S[kt] = acc; }
	v_mfma_f32_32x32x16_bf16 v[32:47], v[68:71], v[140:143], v[32:47]
	ds_read_b128 v[66:69], v66 offset:49152
	s_waitcnt lgkmcnt(0)
	v_mfma_f32_32x32x16_bf16 v[32:47], v[66:69], v[136:139], v[32:47]
	ds_read_b128 v[66:69], v65 offset:49152
	s_waitcnt lgkmcnt(0)
	v_mfma_f32_32x32x16_bf16 v[32:47], v[66:69], v[132:135], v[32:47]
	ds_read_b128 v[64:67], v64 offset:49152
	s_waitcnt lgkmcnt(0)
	v_mfma_f32_32x32x16_bf16 v[32:47], v[64:67], v[128:131], v[32:47]
	v_add_u32_e32 v64, v245, v206
	ds_read_b128 v[64:67], v64
	s_waitcnt lgkmcnt(0)
	v_mfma_f32_32x32x16_bf16 v[64:79], v[64:67], v[112:115], 0
	v_mfma_f32_32x32x16_bf16 v[64:79], v[80:83], v[184:187], v[64:79]
	v_add_u32_e32 v80, v245, v211
	ds_read_b128 v[80:83], v80
	s_waitcnt lgkmcnt(0)
	v_mfma_f32_32x32x16_bf16 v[64:79], v[80:83], v[180:183], v[64:79]
	v_add_u32_e32 v80, v245, v212
	ds_read_b128 v[80:83], v80
	s_waitcnt lgkmcnt(0)
	v_mfma_f32_32x32x16_bf16 v[64:79], v[80:83], v[176:179], v[64:79]
	v_add_u32_e32 v80, v245, v218
	ds_read_b128 v[80:83], v80
	s_waitcnt lgkmcnt(0)
	v_mfma_f32_32x32x16_bf16 v[64:79], v[80:83], v[172:175], v[64:79]
	v_add_u32_e32 v80, v245, v219
	ds_read_b128 v[80:83], v80
	s_waitcnt lgkmcnt(0)
	v_mfma_f32_32x32x16_bf16 v[64:79], v[80:83], v[168:171], v[64:79]
	v_add_u32_e32 v80, v245, v220
	ds_read_b128 v[80:83], v80
	s_waitcnt lgkmcnt(0)
	v_mfma_f32_32x32x16_bf16 v[64:79], v[80:83], v[164:167], v[64:79]
	v_add_u32_e32 v80, v245, v221
	ds_read_b128 v[80:83], v80
	s_waitcnt lgkmcnt(0)
	v_mfma_f32_32x32x16_bf16 v[64:79], v[80:83], v[160:163], v[64:79]
	v_add_u32_e32 v80, v245, v237
	ds_read_b128 v[80:83], v80
	s_waitcnt lgkmcnt(0)
	v_mfma_f32_32x32x16_bf16 v[64:79], v[80:83], v[156:159], v[64:79]
	v_add_u32_e32 v80, v245, v238
	ds_read_b128 v[80:83], v80
	s_waitcnt lgkmcnt(0)
	v_mfma_f32_32x32x16_bf16 v[64:79], v[80:83], v[152:155], v[64:79]
	v_add_u32_e32 v80, v245, v239
	ds_read_b128 v[80:83], v80
	s_waitcnt lgkmcnt(0)
	v_mfma_f32_32x32x16_bf16 v[64:79], v[80:83], v[148:151], v[64:79]
	v_add_u32_e32 v80, v245, v240
	ds_read_b128 v[80:83], v80
	s_waitcnt lgkmcnt(0)
	v_mfma_f32_32x32x16_bf16 v[64:79], v[80:83], v[144:147], v[64:79]
	v_add_u32_e32 v80, v245, v241
	ds_read_b128 v[80:83], v80
	s_waitcnt lgkmcnt(0)
	v_mfma_f32_32x32x16_bf16 v[64:79], v[80:83], v[140:143], v[64:79]
	v_add_u32_e32 v80, v245, v242
	ds_read_b128 v[80:83], v80
	s_waitcnt lgkmcnt(0)
	v_mfma_f32_32x32x16_bf16 v[64:79], v[80:83], v[136:139], v[64:79]
	v_add_u32_e32 v80, v245, v243
	ds_read_b128 v[80:83], v80
	s_waitcnt lgkmcnt(0)
	v_mfma_f32_32x32x16_bf16 v[64:79], v[80:83], v[132:135], v[64:79]
	v_add_u32_e32 v80, v245, v244
	ds_read_b128 v[80:83], v80
	s_waitcnt lgkmcnt(0)
	v_mfma_f32_32x32x16_bf16 v[64:79], v[80:83], v[128:131], v[64:79]
	v_add_u32_e32 v80, v246, v206
	ds_read_b128 v[80:83], v80
	s_waitcnt lgkmcnt(0)
	v_mfma_f32_32x32x16_bf16 v[80:95], v[80:83], v[112:115], 0
	v_mfma_f32_32x32x16_bf16 v[80:95], v[96:99], v[184:187], v[80:95]
	v_add_u32_e32 v96, v246, v211
	ds_read_b128 v[96:99], v96
	s_waitcnt lgkmcnt(0)
	v_mfma_f32_32x32x16_bf16 v[80:95], v[96:99], v[180:183], v[80:95]
	v_add_u32_e32 v96, v246, v212
	ds_read_b128 v[96:99], v96
	s_waitcnt lgkmcnt(0)
	v_mfma_f32_32x32x16_bf16 v[80:95], v[96:99], v[176:179], v[80:95]
	v_add_u32_e32 v96, v246, v218
	ds_read_b128 v[96:99], v96
	s_waitcnt lgkmcnt(0)
	v_mfma_f32_32x32x16_bf16 v[80:95], v[96:99], v[172:175], v[80:95]
	v_add_u32_e32 v96, v246, v219
	ds_read_b128 v[96:99], v96
	s_waitcnt lgkmcnt(0)
	v_mfma_f32_32x32x16_bf16 v[80:95], v[96:99], v[168:171], v[80:95]
	v_add_u32_e32 v96, v246, v220
	ds_read_b128 v[96:99], v96
	s_waitcnt lgkmcnt(0)
	v_mfma_f32_32x32x16_bf16 v[80:95], v[96:99], v[164:167], v[80:95]
	v_add_u32_e32 v96, v246, v221
	ds_read_b128 v[96:99], v96
	s_waitcnt lgkmcnt(0)
	v_mfma_f32_32x32x16_bf16 v[80:95], v[96:99], v[160:163], v[80:95]
	v_add_u32_e32 v96, v246, v237
	ds_read_b128 v[96:99], v96
	s_waitcnt lgkmcnt(0)
	v_mfma_f32_32x32x16_bf16 v[80:95], v[96:99], v[156:159], v[80:95]
	v_add_u32_e32 v96, v246, v238
	ds_read_b128 v[96:99], v96
	s_waitcnt lgkmcnt(0)
	v_mfma_f32_32x32x16_bf16 v[80:95], v[96:99], v[152:155], v[80:95]
	v_add_u32_e32 v96, v246, v239
	ds_read_b128 v[96:99], v96
	s_waitcnt lgkmcnt(0)
	v_mfma_f32_32x32x16_bf16 v[80:95], v[96:99], v[148:151], v[80:95]
	v_add_u32_e32 v96, v246, v240
	ds_read_b128 v[96:99], v96
	s_waitcnt lgkmcnt(0)
	v_mfma_f32_32x32x16_bf16 v[80:95], v[96:99], v[144:147], v[80:95]
	v_add_u32_e32 v96, v246, v241
	ds_read_b128 v[96:99], v96
	s_waitcnt lgkmcnt(0)
	v_mfma_f32_32x32x16_bf16 v[80:95], v[96:99], v[140:143], v[80:95]
	v_add_u32_e32 v96, v246, v242
	ds_read_b128 v[96:99], v96
	s_waitcnt lgkmcnt(0)
	v_mfma_f32_32x32x16_bf16 v[80:95], v[96:99], v[136:139], v[80:95]
	v_add_u32_e32 v96, v246, v243
	ds_read_b128 v[96:99], v96
	s_waitcnt lgkmcnt(0)
	v_mfma_f32_32x32x16_bf16 v[80:95], v[96:99], v[132:135], v[80:95]
	v_add_u32_e32 v96, v246, v244
	ds_read_b128 v[96:99], v96
	s_waitcnt lgkmcnt(0)
	v_mfma_f32_32x32x16_bf16 v[80:95], v[96:99], v[128:131], v[80:95]
	v_add_u32_e32 v96, v247, v206
	ds_read_b128 v[96:99], v96
	s_waitcnt lgkmcnt(0)
	v_mfma_f32_32x32x16_bf16 v[96:111], v[96:99], v[112:115], 0
	v_mfma_f32_32x32x16_bf16 v[96:111], v[116:119], v[184:187], v[96:111]
	v_add_u32_e32 v116, v247, v211
	ds_read_b128 v[116:119], v116
	s_waitcnt lgkmcnt(0)
	v_mfma_f32_32x32x16_bf16 v[96:111], v[116:119], v[180:183], v[96:111]
	v_add_u32_e32 v116, v247, v212
	ds_read_b128 v[116:119], v116
	s_waitcnt lgkmcnt(0)
	v_mfma_f32_32x32x16_bf16 v[96:111], v[116:119], v[176:179], v[96:111]
	v_add_u32_e32 v116, v247, v218
	ds_read_b128 v[116:119], v116
	s_waitcnt lgkmcnt(0)
; __device__ __forceinline__ float shx(float v, int lane, int mask) { return __builtin_bit_cast(float, __builtin_amdgcn_ds_bpermute((lane ^ mask) << 2, __builtin_bit_cast(int, v))); }
; #define LAS __attribute__((address_space(3)))
; __device__ __forceinline__ void xattn_unit(LAS unsigned char* lds, const bf16_t* Qx, const bf16_t* KV, int li, int b, int h, int qb, bf16_t* XO, const int tid) {
;     ...
;     for (int kt = 0; kt < 8; ++kt) { f32x16 acc = {}; const lds_cptr kp = (lds_cptr)lds + (32 * kt + r32) * 512;
; #pragma unroll
;         for (int s = 0; s < 16; ++s) { const bf16x8 kf = *(const LAS bf16x8*)(kp + (((2 * s + hi) ^ (r32 & 15)) << 4)); acc = __builtin_amdgcn_mfma_f32_32x32x16_bf16(kf, qf[s], acc, 0, 0, 0); }
;         S[kt] = acc; }
;     float m = S[0][0];
; #pragma unroll
;     for (int kt = 0; kt < 8; ++kt)
; #pragma unroll
;         for (int r = 0; r < 16; ++r) m = fmaxf(m, S[kt][r]);
;     m = fmaxf(m, pg8::shx(m, lane, 32));
	v_mfma_f32_32x32x16_bf16 v[96:111], v[116:119], v[172:175], v[96:111]
	v_add_u32_e32 v116, v247, v219
	ds_read_b128 v[116:119], v116
	s_waitcnt lgkmcnt(0)
	v_mfma_f32_32x32x16_bf16 v[96:111], v[116:119], v[168:171], v[96:111]
	v_add_u32_e32 v116, v247, v220
	ds_read_b128 v[116:119], v116
	s_waitcnt lgkmcnt(0)
	v_mfma_f32_32x32x16_bf16 v[96:111], v[116:119], v[164:167], v[96:111]
	v_add_u32_e32 v116, v247, v221
	ds_read_b128 v[116:119], v116
	s_waitcnt lgkmcnt(0)
	v_mfma_f32_32x32x16_bf16 v[96:111], v[116:119], v[160:163], v[96:111]
	v_add_u32_e32 v116, v247, v237
	ds_read_b128 v[116:119], v116
	s_waitcnt lgkmcnt(0)
	v_mfma_f32_32x32x16_bf16 v[96:111], v[116:119], v[156:159], v[96:111]
	v_add_u32_e32 v116, v247, v238
	ds_read_b128 v[116:119], v116
	s_waitcnt lgkmcnt(0)
	v_mfma_f32_32x32x16_bf16 v[96:111], v[116:119], v[152:155], v[96:111]
	v_add_u32_e32 v116, v247, v239
	ds_read_b128 v[116:119], v116
	s_waitcnt lgkmcnt(0)
	v_mfma_f32_32x32x16_bf16 v[96:111], v[116:119], v[148:151], v[96:111]
	v_add_u32_e32 v116, v247, v240
	ds_read_b128 v[116:119], v116
	s_waitcnt lgkmcnt(0)
	v_mfma_f32_32x32x16_bf16 v[96:111], v[116:119], v[144:147], v[96:111]
	v_add_u32_e32 v116, v247, v241
	ds_read_b128 v[116:119], v116
	s_waitcnt lgkmcnt(0)
	v_mfma_f32_32x32x16_bf16 v[96:111], v[116:119], v[140:143], v[96:111]
	v_add_u32_e32 v116, v247, v242
	ds_read_b128 v[116:119], v116
	s_waitcnt lgkmcnt(0)
	v_mfma_f32_32x32x16_bf16 v[96:111], v[116:119], v[136:139], v[96:111]
	v_add_u32_e32 v116, v247, v243
	ds_read_b128 v[116:119], v116
	s_waitcnt lgkmcnt(0)
	v_mfma_f32_32x32x16_bf16 v[96:111], v[116:119], v[132:135], v[96:111]
	v_add_u32_e32 v116, v247, v244
	ds_read_b128 v[116:119], v116
	s_waitcnt lgkmcnt(0)
	v_mfma_f32_32x32x16_bf16 v[96:111], v[116:119], v[128:131], v[96:111]
	v_add_u32_e32 v116, v248, v206
	ds_read_b128 v[116:119], v116
	s_waitcnt lgkmcnt(0)
	v_mfma_f32_32x32x16_bf16 v[112:127], v[116:119], v[112:115], 0
	v_mfma_f32_32x32x16_bf16 v[112:127], v[222:225], v[184:187], v[112:127]
	v_add_u32_e32 v184, v248, v211
	ds_read_b128 v[184:187], v184
	s_waitcnt lgkmcnt(0)
	v_mfma_f32_32x32x16_bf16 v[112:127], v[184:187], v[180:183], v[112:127]
	v_add_u32_e32 v180, v248, v212
	ds_read_b128 v[180:183], v180
	s_waitcnt lgkmcnt(0)
	v_mfma_f32_32x32x16_bf16 v[112:127], v[180:183], v[176:179], v[112:127]
	v_add_u32_e32 v176, v248, v218
	ds_read_b128 v[176:179], v176
	s_waitcnt lgkmcnt(0)
	v_mfma_f32_32x32x16_bf16 v[112:127], v[176:179], v[172:175], v[112:127]
	v_add_u32_e32 v172, v248, v219
	ds_read_b128 v[172:175], v172
	s_waitcnt lgkmcnt(0)
	v_mfma_f32_32x32x16_bf16 v[112:127], v[172:175], v[168:171], v[112:127]
	v_add_u32_e32 v168, v248, v220
	ds_read_b128 v[168:171], v168
	s_waitcnt lgkmcnt(0)
	v_mfma_f32_32x32x16_bf16 v[112:127], v[168:171], v[164:167], v[112:127]
	v_add_u32_e32 v164, v248, v221
	ds_read_b128 v[164:167], v164
	s_waitcnt lgkmcnt(0)
	v_mfma_f32_32x32x16_bf16 v[112:127], v[164:167], v[160:163], v[112:127]
	v_add_u32_e32 v160, v248, v237
	ds_read_b128 v[160:163], v160
	s_waitcnt lgkmcnt(0)
	v_mfma_f32_32x32x16_bf16 v[112:127], v[160:163], v[156:159], v[112:127]
	v_add_u32_e32 v156, v248, v238
	ds_read_b128 v[156:159], v156
	s_waitcnt lgkmcnt(0)
	v_mfma_f32_32x32x16_bf16 v[112:127], v[156:159], v[152:155], v[112:127]
	v_add_u32_e32 v152, v248, v239
	ds_read_b128 v[152:155], v152
	s_waitcnt lgkmcnt(0)
	v_mfma_f32_32x32x16_bf16 v[112:127], v[152:155], v[148:151], v[112:127]
	v_add_u32_e32 v148, v248, v240
	ds_read_b128 v[148:151], v148
	s_waitcnt lgkmcnt(0)
	v_mfma_f32_32x32x16_bf16 v[112:127], v[148:151], v[144:147], v[112:127]
	v_add_u32_e32 v144, v248, v241
	ds_read_b128 v[144:147], v144
	s_waitcnt lgkmcnt(0)
	v_mfma_f32_32x32x16_bf16 v[112:127], v[144:147], v[140:143], v[112:127]
	v_add_u32_e32 v140, v248, v242
	ds_read_b128 v[140:143], v140
	s_waitcnt lgkmcnt(0)
	v_mfma_f32_32x32x16_bf16 v[112:127], v[140:143], v[136:139], v[112:127]
	v_add_u32_e32 v136, v248, v243
	ds_read_b128 v[136:139], v136
	s_waitcnt lgkmcnt(0)
	v_mfma_f32_32x32x16_bf16 v[112:127], v[136:139], v[132:135], v[112:127]
	v_add_u32_e32 v132, v248, v244
	ds_read_b128 v[132:135], v132
	s_waitcnt lgkmcnt(0)
	v_mfma_f32_32x32x16_bf16 v[112:127], v[132:135], v[128:131], v[112:127]
	v_max_f32_e32 v128, v1, v1
	v_max_f32_e32 v129, v0, v0
	v_max_f32_e32 v128, v129, v128
	v_max3_f32 v128, v128, v2, v3
	v_max3_f32 v128, v128, v4, v5
	v_max3_f32 v128, v128, v6, v7
	v_max3_f32 v128, v128, v8, v9
	v_max3_f32 v128, v128, v10, v11
	v_max3_f32 v128, v128, v12, v13
	v_max3_f32 v128, v128, v14, v15
	v_max3_f32 v128, v128, v16, v17
	v_max3_f32 v128, v128, v18, v19
	v_max3_f32 v128, v128, v20, v21
	v_max3_f32 v128, v128, v22, v23
	v_max3_f32 v128, v128, v24, v25
	v_max3_f32 v128, v128, v26, v27
	v_max3_f32 v128, v128, v28, v29
	v_max3_f32 v128, v128, v30, v31
	v_max3_f32 v128, v128, v48, v49
	v_max3_f32 v128, v128, v50, v51
	v_max3_f32 v128, v128, v52, v53
	v_max3_f32 v128, v128, v54, v55
	v_max3_f32 v128, v128, v56, v57
	v_max3_f32 v128, v128, v58, v59
	v_max3_f32 v128, v128, v60, v61
	v_max3_f32 v128, v128, v62, v63
	v_max3_f32 v128, v128, v32, v33
	v_max3_f32 v128, v128, v34, v35
	v_max3_f32 v128, v128, v36, v37
	v_max3_f32 v128, v128, v38, v39
	v_max3_f32 v128, v128, v40, v41
	v_max3_f32 v128, v128, v42, v43
	v_max3_f32 v128, v128, v44, v45
	v_max3_f32 v128, v128, v46, v47
	v_max3_f32 v128, v128, v64, v65
	v_max3_f32 v128, v128, v66, v67
	v_max3_f32 v128, v128, v68, v69
	v_max3_f32 v128, v128, v70, v71
	v_max3_f32 v128, v128, v72, v73
	v_max3_f32 v128, v128, v74, v75
	v_max3_f32 v128, v128, v76, v77
	v_max3_f32 v128, v128, v78, v79
	v_max3_f32 v128, v128, v80, v81
	v_max3_f32 v128, v128, v82, v83
	v_max3_f32 v128, v128, v84, v85
	v_max3_f32 v128, v128, v86, v87
	v_max3_f32 v128, v128, v88, v89
	v_max3_f32 v128, v128, v90, v91
	v_max3_f32 v128, v128, v92, v93
	v_max3_f32 v128, v128, v94, v95
	v_max3_f32 v128, v128, v96, v97
	v_max3_f32 v128, v128, v98, v99
	v_max3_f32 v128, v128, v100, v101
	v_max3_f32 v128, v128, v102, v103
	v_max3_f32 v128, v128, v104, v105
	v_max3_f32 v128, v128, v106, v107
	v_max3_f32 v128, v128, v108, v109
	v_max3_f32 v128, v128, v110, v111
	v_max3_f32 v128, v128, v112, v113
	v_max3_f32 v128, v128, v114, v115
	v_max3_f32 v128, v128, v116, v117
	v_max3_f32 v128, v128, v118, v119
	v_max3_f32 v128, v128, v120, v121
	v_max3_f32 v128, v128, v122, v123
	v_max3_f32 v128, v128, v124, v125
	v_max3_f32 v128, v128, v126, v127
	ds_bpermute_b32 v129, v249, v128
	s_waitcnt lgkmcnt(0)
; __device__ __forceinline__ float shx(float v, int lane, int mask) { return __builtin_bit_cast(float, __builtin_amdgcn_ds_bpermute((lane ^ mask) << 2, __builtin_bit_cast(int, v))); }
; __device__ __forceinline__ void xattn_unit(LAS unsigned char* lds, const bf16_t* Qx, const bf16_t* KV, int li, int b, int h, int qb, bf16_t* XO, const int tid) {
;     ...
;     m = fmaxf(m, pg8::shx(m, lane, 32));
;     float l = 0.f;
; #pragma unroll
;     for (int kt = 0; kt < 8; ++kt)
; #pragma unroll
;         for (int r = 0; r < 16; ++r) { const float p = __builtin_amdgcn_exp2f(S[kt][r] - m); S[kt][r] = p; l += p; }
	v_max_f32_e32 v129, v129, v129
	v_max_f32_e32 v128, v128, v129
	v_sub_f32_e32 v0, v0, v128
	v_exp_f32_e32 v0, v0
	v_sub_f32_e32 v1, v1, v128
	v_exp_f32_e32 v1, v1
	v_sub_f32_e32 v2, v2, v128
	v_exp_f32_e32 v2, v2
	v_sub_f32_e32 v3, v3, v128
	v_exp_f32_e32 v3, v3
	v_sub_f32_e32 v4, v4, v128
	v_add_f32_e32 v129, 0, v0
	v_exp_f32_e32 v4, v4
	v_sub_f32_e32 v5, v5, v128
	v_add_f32_e32 v129, v1, v129
	v_exp_f32_e32 v5, v5
	v_sub_f32_e32 v6, v6, v128
	v_add_f32_e32 v129, v2, v129
	v_exp_f32_e32 v6, v6
	v_sub_f32_e32 v7, v7, v128
	v_add_f32_e32 v129, v3, v129
	v_exp_f32_e32 v7, v7
	v_sub_f32_e32 v8, v8, v128
	v_add_f32_e32 v129, v4, v129
	v_exp_f32_e32 v8, v8
	v_sub_f32_e32 v9, v9, v128
	v_add_f32_e32 v129, v5, v129
	v_exp_f32_e32 v9, v9
	v_sub_f32_e32 v10, v10, v128
	v_add_f32_e32 v129, v6, v129
	v_exp_f32_e32 v10, v10
	v_sub_f32_e32 v11, v11, v128
	v_add_f32_e32 v129, v7, v129
	v_exp_f32_e32 v11, v11
	v_sub_f32_e32 v12, v12, v128
	v_add_f32_e32 v129, v8, v129
	v_exp_f32_e32 v12, v12
	v_sub_f32_e32 v13, v13, v128
	v_add_f32_e32 v129, v9, v129
	v_exp_f32_e32 v13, v13
	v_sub_f32_e32 v14, v14, v128
	v_add_f32_e32 v129, v10, v129
	v_exp_f32_e32 v14, v14
	v_sub_f32_e32 v15, v15, v128
	v_add_f32_e32 v129, v11, v129
	v_exp_f32_e32 v15, v15
	v_add_f32_e32 v129, v12, v129
	v_add_f32_e32 v129, v13, v129
	v_add_f32_e32 v129, v14, v129
	v_sub_f32_e32 v16, v16, v128
	v_add_f32_e32 v130, v15, v129
	v_exp_f32_e32 v129, v16
	v_sub_f32_e32 v17, v17, v128
	v_add_f32_e32 v16, v129, v130
	v_exp_f32_e32 v130, v17
	v_sub_f32_e32 v17, v18, v128
	v_exp_f32_e32 v131, v17
	v_sub_f32_e32 v17, v19, v128
	v_exp_f32_e32 v132, v17
	v_sub_f32_e32 v17, v20, v128
	v_exp_f32_e32 v133, v17
	v_sub_f32_e32 v17, v21, v128
	v_add_f32_e32 v16, v130, v16
	v_exp_f32_e32 v134, v17
	v_sub_f32_e32 v17, v22, v128
	v_add_f32_e32 v16, v131, v16
	v_exp_f32_e32 v135, v17
	v_sub_f32_e32 v17, v23, v128
	v_add_f32_e32 v16, v132, v16
	v_exp_f32_e32 v136, v17
	v_sub_f32_e32 v17, v24, v128
	v_add_f32_e32 v16, v133, v16
	v_exp_f32_e32 v137, v17
	v_sub_f32_e32 v17, v25, v128
	v_add_f32_e32 v16, v134, v16
	v_exp_f32_e32 v138, v17
	v_sub_f32_e32 v17, v26, v128
	v_add_f32_e32 v16, v135, v16
	v_exp_f32_e32 v139, v17
	v_sub_f32_e32 v17, v27, v128
	v_add_f32_e32 v16, v136, v16
	v_exp_f32_e32 v140, v17
	v_sub_f32_e32 v17, v28, v128
	v_add_f32_e32 v16, v137, v16
	v_exp_f32_e32 v141, v17
	v_sub_f32_e32 v17, v29, v128
	v_add_f32_e32 v16, v138, v16
	v_exp_f32_e32 v142, v17
	v_sub_f32_e32 v17, v30, v128
	v_add_f32_e32 v16, v139, v16
	v_exp_f32_e32 v143, v17
	v_sub_f32_e32 v17, v31, v128
	v_add_f32_e32 v16, v140, v16
	v_exp_f32_e32 v31, v17
	v_sub_f32_e32 v17, v48, v128
	v_add_f32_e32 v16, v141, v16
	v_exp_f32_e32 v48, v17
	v_sub_f32_e32 v17, v49, v128
	v_add_f32_e32 v16, v142, v16
	v_exp_f32_e32 v49, v17
	v_sub_f32_e32 v17, v50, v128
	v_add_f32_e32 v16, v143, v16
	v_exp_f32_e32 v50, v17
	v_sub_f32_e32 v17, v51, v128
	v_add_f32_e32 v16, v31, v16
	v_exp_f32_e32 v51, v17
	v_sub_f32_e32 v17, v52, v128
	v_add_f32_e32 v16, v48, v16
	v_exp_f32_e32 v52, v17
	v_sub_f32_e32 v17, v53, v128
	v_add_f32_e32 v16, v49, v16
	v_exp_f32_e32 v53, v17
	v_sub_f32_e32 v17, v54, v128
	v_add_f32_e32 v16, v50, v16
	v_exp_f32_e32 v54, v17
	v_sub_f32_e32 v17, v55, v128
	v_add_f32_e32 v16, v51, v16
	v_exp_f32_e32 v55, v17
	v_sub_f32_e32 v17, v56, v128
	v_add_f32_e32 v16, v52, v16
	v_exp_f32_e32 v56, v17
	v_sub_f32_e32 v17, v57, v128
	v_add_f32_e32 v16, v53, v16
	v_exp_f32_e32 v57, v17
	v_sub_f32_e32 v17, v58, v128
	v_add_f32_e32 v16, v54, v16
	v_exp_f32_e32 v58, v17
	v_sub_f32_e32 v17, v59, v128
	v_add_f32_e32 v16, v55, v16
	v_exp_f32_e32 v59, v17
	v_sub_f32_e32 v17, v60, v128
	v_add_f32_e32 v16, v56, v16
	v_exp_f32_e32 v60, v17
	v_sub_f32_e32 v17, v61, v128
	v_add_f32_e32 v16, v57, v16
	v_exp_f32_e32 v61, v17
	v_sub_f32_e32 v17, v62, v128
	v_add_f32_e32 v16, v58, v16
	v_exp_f32_e32 v62, v17
	v_sub_f32_e32 v17, v63, v128
	v_add_f32_e32 v16, v59, v16
	v_exp_f32_e32 v63, v17
	v_sub_f32_e32 v17, v32, v128
	v_add_f32_e32 v16, v60, v16
	v_exp_f32_e32 v144, v17
	v_sub_f32_e32 v17, v33, v128
	v_add_f32_e32 v16, v61, v16
	v_exp_f32_e32 v145, v17
	v_sub_f32_e32 v17, v34, v128
	v_add_f32_e32 v16, v62, v16
	v_exp_f32_e32 v146, v17
	v_sub_f32_e32 v17, v35, v128
	v_add_f32_e32 v16, v63, v16
	v_exp_f32_e32 v147, v17
	v_sub_f32_e32 v17, v36, v128
	v_add_f32_e32 v16, v144, v16
	v_exp_f32_e32 v148, v17
	v_sub_f32_e32 v17, v37, v128
	v_add_f32_e32 v16, v145, v16
	v_exp_f32_e32 v149, v17
	v_sub_f32_e32 v17, v38, v128
	v_add_f32_e32 v16, v146, v16
	v_exp_f32_e32 v150, v17
	v_sub_f32_e32 v17, v39, v128
	v_add_f32_e32 v16, v147, v16
	v_exp_f32_e32 v151, v17
	v_sub_f32_e32 v17, v40, v128
	v_add_f32_e32 v16, v148, v16
	v_exp_f32_e32 v152, v17
	v_sub_f32_e32 v17, v41, v128
	v_add_f32_e32 v16, v149, v16
	v_exp_f32_e32 v153, v17
	v_sub_f32_e32 v17, v42, v128
	v_add_f32_e32 v16, v150, v16
	v_exp_f32_e32 v154, v17
	v_sub_f32_e32 v17, v43, v128
	v_add_f32_e32 v16, v151, v16
	v_exp_f32_e32 v155, v17
	v_sub_f32_e32 v17, v44, v128
	v_add_f32_e32 v16, v152, v16
	v_exp_f32_e32 v156, v17
	v_sub_f32_e32 v17, v45, v128
	v_add_f32_e32 v16, v153, v16
	v_exp_f32_e32 v157, v17
	v_sub_f32_e32 v17, v46, v128
	v_add_f32_e32 v16, v154, v16
	v_exp_f32_e32 v158, v17
	v_sub_f32_e32 v17, v47, v128
	v_add_f32_e32 v16, v155, v16
	v_exp_f32_e32 v47, v17
	v_sub_f32_e32 v17, v64, v128
	v_add_f32_e32 v16, v156, v16
	v_exp_f32_e32 v64, v17
	v_sub_f32_e32 v17, v65, v128
	v_add_f32_e32 v16, v157, v16
	v_exp_f32_e32 v65, v17
	v_sub_f32_e32 v17, v66, v128
	v_add_f32_e32 v16, v158, v16
	v_exp_f32_e32 v66, v17
	v_sub_f32_e32 v17, v67, v128
	v_add_f32_e32 v16, v47, v16
	v_exp_f32_e32 v67, v17
; __device__ __forceinline__ float shx(float v, int lane, int mask) { return __builtin_bit_cast(float, __builtin_amdgcn_ds_bpermute((lane ^ mask) << 2, __builtin_bit_cast(int, v))); }
; __device__ __forceinline__ void xattn_unit(LAS unsigned char* lds, const bf16_t* Qx, const bf16_t* KV, int li, int b, int h, int qb, bf16_t* XO, const int tid) {
;     ...
;         for (int r = 0; r < 16; ++r) { const float p = __builtin_amdgcn_exp2f(S[kt][r] - m); S[kt][r] = p; l += p; }
;     l += pg8::shx(l, lane, 32);
;     const float inv = __builtin_amdgcn_rcpf(l);
;     bf16x8 pf[16];
; #pragma unroll
;     for (int kt = 0; kt < 8; ++kt) { pf[2 * kt] = pack8(S[kt], 0); pf[2 * kt + 1] = pack8(S[kt], 8); }
	v_sub_f32_e32 v17, v68, v128
	v_add_f32_e32 v16, v64, v16
	v_exp_f32_e32 v68, v17
	v_sub_f32_e32 v17, v69, v128
	v_add_f32_e32 v16, v65, v16
	v_exp_f32_e32 v69, v17
	v_sub_f32_e32 v17, v70, v128
	v_add_f32_e32 v16, v66, v16
	v_exp_f32_e32 v70, v17
	v_sub_f32_e32 v17, v71, v128
	v_add_f32_e32 v16, v67, v16
	v_exp_f32_e32 v71, v17
	v_sub_f32_e32 v17, v72, v128
	v_add_f32_e32 v16, v68, v16
	v_exp_f32_e32 v72, v17
	v_sub_f32_e32 v17, v73, v128
	v_add_f32_e32 v16, v69, v16
	v_exp_f32_e32 v73, v17
	v_sub_f32_e32 v17, v74, v128
	v_add_f32_e32 v16, v70, v16
	v_exp_f32_e32 v74, v17
	v_sub_f32_e32 v17, v75, v128
	v_add_f32_e32 v16, v71, v16
	v_exp_f32_e32 v75, v17
	v_sub_f32_e32 v17, v76, v128
	v_add_f32_e32 v16, v72, v16
	v_exp_f32_e32 v76, v17
	v_sub_f32_e32 v17, v77, v128
	v_add_f32_e32 v16, v73, v16
	v_exp_f32_e32 v77, v17
	v_sub_f32_e32 v17, v78, v128
	v_add_f32_e32 v16, v74, v16
	v_exp_f32_e32 v78, v17
	v_sub_f32_e32 v17, v79, v128
	v_add_f32_e32 v16, v75, v16
	v_exp_f32_e32 v79, v17
	v_sub_f32_e32 v17, v80, v128
	v_add_f32_e32 v16, v76, v16
	v_exp_f32_e32 v159, v17
	v_sub_f32_e32 v17, v81, v128
	v_add_f32_e32 v16, v77, v16
	v_exp_f32_e32 v160, v17
	v_sub_f32_e32 v17, v82, v128
	v_add_f32_e32 v16, v78, v16
	v_exp_f32_e32 v82, v17
	v_sub_f32_e32 v17, v83, v128
	v_add_f32_e32 v16, v79, v16
	v_exp_f32_e32 v83, v17
	v_sub_f32_e32 v17, v84, v128
	v_add_f32_e32 v16, v159, v16
	v_exp_f32_e32 v84, v17
	v_sub_f32_e32 v17, v85, v128
	v_add_f32_e32 v16, v160, v16
	v_exp_f32_e32 v85, v17
	v_sub_f32_e32 v17, v86, v128
	v_add_f32_e32 v16, v82, v16
	v_exp_f32_e32 v86, v17
	v_sub_f32_e32 v17, v87, v128
	v_add_f32_e32 v16, v83, v16
	v_exp_f32_e32 v87, v17
	v_sub_f32_e32 v17, v88, v128
	v_add_f32_e32 v16, v84, v16
	v_exp_f32_e32 v88, v17
	v_sub_f32_e32 v17, v89, v128
	v_add_f32_e32 v16, v85, v16
	v_exp_f32_e32 v89, v17
	v_sub_f32_e32 v17, v90, v128
	v_add_f32_e32 v16, v86, v16
	v_exp_f32_e32 v90, v17
	v_sub_f32_e32 v17, v91, v128
	v_add_f32_e32 v16, v87, v16
	v_exp_f32_e32 v91, v17
	v_sub_f32_e32 v17, v92, v128
	v_add_f32_e32 v16, v88, v16
	v_exp_f32_e32 v92, v17
	v_sub_f32_e32 v17, v93, v128
	v_add_f32_e32 v16, v89, v16
	v_exp_f32_e32 v93, v17
	v_sub_f32_e32 v17, v94, v128
	v_add_f32_e32 v16, v90, v16
	v_exp_f32_e32 v94, v17
	v_sub_f32_e32 v17, v95, v128
	v_add_f32_e32 v16, v91, v16
	v_exp_f32_e32 v95, v17
	v_sub_f32_e32 v17, v96, v128
	v_add_f32_e32 v16, v92, v16
	v_exp_f32_e32 v96, v17
	v_sub_f32_e32 v17, v97, v128
	v_add_f32_e32 v16, v93, v16
	v_exp_f32_e32 v97, v17
	v_sub_f32_e32 v17, v98, v128
	v_add_f32_e32 v16, v94, v16
	v_exp_f32_e32 v98, v17
	v_sub_f32_e32 v17, v99, v128
	v_add_f32_e32 v16, v95, v16
	v_exp_f32_e32 v99, v17
	v_sub_f32_e32 v17, v100, v128
	v_add_f32_e32 v16, v96, v16
	v_exp_f32_e32 v100, v17
	v_sub_f32_e32 v17, v101, v128
	v_add_f32_e32 v16, v97, v16
	v_exp_f32_e32 v101, v17
	v_sub_f32_e32 v17, v102, v128
	v_add_f32_e32 v16, v98, v16
	v_exp_f32_e32 v102, v17
	v_sub_f32_e32 v17, v103, v128
	v_add_f32_e32 v16, v99, v16
	v_exp_f32_e32 v103, v17
	v_sub_f32_e32 v17, v104, v128
	v_add_f32_e32 v16, v100, v16
	v_exp_f32_e32 v104, v17
	v_sub_f32_e32 v17, v105, v128
	v_add_f32_e32 v16, v101, v16
	v_exp_f32_e32 v105, v17
	v_sub_f32_e32 v17, v106, v128
	v_add_f32_e32 v16, v102, v16
	v_exp_f32_e32 v106, v17
	v_sub_f32_e32 v17, v107, v128
	v_add_f32_e32 v16, v103, v16
	v_exp_f32_e32 v107, v17
	v_sub_f32_e32 v17, v108, v128
	v_add_f32_e32 v16, v104, v16
	v_exp_f32_e32 v108, v17
	v_sub_f32_e32 v17, v109, v128
	v_add_f32_e32 v16, v105, v16
	v_exp_f32_e32 v109, v17
	v_sub_f32_e32 v17, v110, v128
	v_add_f32_e32 v16, v106, v16
	v_exp_f32_e32 v110, v17
	v_sub_f32_e32 v17, v111, v128
	v_add_f32_e32 v16, v107, v16
	v_exp_f32_e32 v111, v17
	v_sub_f32_e32 v17, v112, v128
	v_add_f32_e32 v16, v108, v16
	v_exp_f32_e32 v112, v17
	v_sub_f32_e32 v17, v113, v128
	v_add_f32_e32 v16, v109, v16
	v_exp_f32_e32 v113, v17
	v_sub_f32_e32 v17, v114, v128
	v_add_f32_e32 v16, v110, v16
	v_exp_f32_e32 v114, v17
	v_sub_f32_e32 v17, v115, v128
	v_add_f32_e32 v16, v111, v16
	v_exp_f32_e32 v115, v17
	v_sub_f32_e32 v17, v116, v128
	v_add_f32_e32 v16, v112, v16
	v_exp_f32_e32 v116, v17
	v_sub_f32_e32 v17, v117, v128
	v_add_f32_e32 v16, v113, v16
	v_exp_f32_e32 v117, v17
	v_sub_f32_e32 v17, v118, v128
	v_add_f32_e32 v16, v114, v16
	v_exp_f32_e32 v118, v17
	v_sub_f32_e32 v17, v119, v128
	v_add_f32_e32 v16, v115, v16
	v_exp_f32_e32 v119, v17
	v_sub_f32_e32 v17, v120, v128
	v_add_f32_e32 v16, v116, v16
	v_exp_f32_e32 v120, v17
	v_sub_f32_e32 v17, v121, v128
	v_add_f32_e32 v16, v117, v16
	v_exp_f32_e32 v121, v17
	v_sub_f32_e32 v17, v122, v128
	v_add_f32_e32 v16, v118, v16
	v_exp_f32_e32 v122, v17
	v_sub_f32_e32 v17, v123, v128
	v_add_f32_e32 v16, v119, v16
	v_exp_f32_e32 v123, v17
	v_sub_f32_e32 v17, v124, v128
	v_add_f32_e32 v16, v120, v16
	v_exp_f32_e32 v124, v17
	v_sub_f32_e32 v17, v125, v128
	v_add_f32_e32 v16, v121, v16
	v_exp_f32_e32 v125, v17
	v_sub_f32_e32 v17, v126, v128
	v_add_f32_e32 v16, v122, v16
	v_exp_f32_e32 v126, v17
	v_sub_f32_e32 v17, v127, v128
	v_add_f32_e32 v16, v123, v16
	v_exp_f32_e32 v127, v17
	v_add_f32_e32 v16, v124, v16
	v_add_f32_e32 v16, v125, v16
	v_add_f32_e32 v16, v126, v16
	v_add_f32_e32 v80, v127, v16
	ds_bpermute_b32 v81, v249, v80
	v_cvt_pk_bf16_f32 v16, v0, v1
	v_cvt_pk_bf16_f32 v17, v2, v3
	v_cvt_pk_bf16_f32 v18, v4, v5
	v_cvt_pk_bf16_f32 v19, v6, v7
	v_cvt_pk_bf16_f32 v20, v8, v9
	v_cvt_pk_bf16_f32 v21, v10, v11
	v_cvt_pk_bf16_f32 v22, v12, v13
	v_cvt_pk_bf16_f32 v23, v14, v15
	v_cvt_pk_bf16_f32 v24, v129, v130
	v_cvt_pk_bf16_f32 v25, v131, v132
	v_cvt_pk_bf16_f32 v26, v133, v134
	v_cvt_pk_bf16_f32 v27, v135, v136
	v_cvt_pk_bf16_f32 v28, v137, v138
; __device__ __forceinline__ v4i16_t vtr(lds_cptr p) { return __builtin_amdgcn_ds_read_tr16_b64_v4i16((LAS v4i16_t*)p); }
; template <bool MERGE> __device__ __forceinline__ void store_ot(const f32x16& acc, float sc, bf16_t* rowp  , int hi, float wa, float wb, const u32x4 (&oldv)[2]) {
;     ...
;     for (int g = 0; g < 4; ++g) { w[2 * g] = pkbf(acc[4 * g] * sc, acc[4 * g + 1] * sc); w[2 * g + 1] = pkbf(acc[4 * g + 2] * sc, acc[4 * g + 3] * sc); }
; #pragma unroll
;     for (int g = 0; g < 4; g += 2) {
;         const auto rx = __builtin_amdgcn_permlane32_swap(w[2 * g], w[2 * g + 2], false, false);
;         const auto ry = __builtin_amdgcn_permlane32_swap(w[2 * g + 1], w[2 * g + 3], false, false);
;         u32x4 o; o.x = rx[0]; o.y = ry[0]; o.z = rx[1]; o.w = ry[1];
;         u32x4* dst = (u32x4*)(rowp + 8 * g + (hi ? 8 : 0));
;         if (MERGE) { const u32x4 old = oldv[g >> 1];
;     ...
;             o.x = ATT_MRG(o.x, old.x); o.y = ATT_MRG(o.y, old.y); o.z = ATT_MRG(o.z, old.z); o.w = ATT_MRG(o.w, old.w);
;     ...
;         }
;         *dst = o;
; __device__ __forceinline__ void xattn_unit(LAS unsigned char* lds, const bf16_t* Qx, const bf16_t* KV, int li, int b, int h, int qb, bf16_t* XO, const int tid) {
;     ...
;     for (int kt = 0; kt < 8; ++kt) { pf[2 * kt] = pack8(S[kt], 0); pf[2 * kt + 1] = pack8(S[kt], 8); }
;     ATT_SYNC();
;     const bf16_t* Vb = Kb + 1024;
; #pragma unroll 4
;     for (int ii = 0; ii < 16; ++ii) { const int i = wid * 16 + ii, d0 = i >> 4, ks = i & 15, key = 16 * ks + 8 * hi + ((lane >> 2) & 7), cc = lane & 3;
;         glds16(Vb + (size_t)key * 8192 + 32 * d0 + 8 * cc, lds + i * 1024); }
;     ATT_SYNC();
;     const lds_cptr vb = (lds_cptr)lds + ((lane >> 4) & 1) * 32 + (lane & 3) * 8 + (4 * hi + ((lane & 15) >> 2)) * 64;
;     bf16_t* orow = XO + tok * 1024 + h * 256;
; #pragma unroll 1
;     for (int d0 = 0; d0 < 8; ++d0) { f32x16 acc = {};
; #pragma unroll
;         for (int ks = 0; ks < 16; ++ks) { const v4i16_t lo = vtr(vb + d0 * 16384 + ks * 1024), hh = vtr(vb + d0 * 16384 + ks * 1024 + 512);
;             const bf16x8 vf = {lo[0], lo[1], lo[2], lo[3], hh[0], hh[1], hh[2], hh[3]};
;             acc = __builtin_amdgcn_mfma_f32_32x32x16_bf16(vf, pf[ks], acc, 0, 0, 0); }
;         const u32x4 none[2] = {}; store_ot<false>(acc, inv, orow + 32 * d0, hi, 0.f, 0.f, none); }
	v_cvt_pk_bf16_f32 v29, v139, v140
	v_cvt_pk_bf16_f32 v30, v141, v142
	v_cvt_pk_bf16_f32 v31, v143, v31
	v_cvt_pk_bf16_f32 v32, v48, v49
	v_cvt_pk_bf16_f32 v33, v50, v51
	v_cvt_pk_bf16_f32 v34, v52, v53
	v_cvt_pk_bf16_f32 v35, v54, v55
	v_cvt_pk_bf16_f32 v36, v56, v57
	v_cvt_pk_bf16_f32 v37, v58, v59
	v_cvt_pk_bf16_f32 v38, v60, v61
	v_cvt_pk_bf16_f32 v39, v62, v63
	v_cvt_pk_bf16_f32 v40, v144, v145
	v_cvt_pk_bf16_f32 v41, v146, v147
	v_cvt_pk_bf16_f32 v42, v148, v149
	v_cvt_pk_bf16_f32 v43, v150, v151
	v_cvt_pk_bf16_f32 v44, v152, v153
	v_cvt_pk_bf16_f32 v45, v154, v155
	v_cvt_pk_bf16_f32 v46, v156, v157
	v_cvt_pk_bf16_f32 v47, v158, v47
	v_cvt_pk_bf16_f32 v48, v64, v65
	v_cvt_pk_bf16_f32 v49, v66, v67
	v_cvt_pk_bf16_f32 v50, v68, v69
	v_cvt_pk_bf16_f32 v51, v70, v71
	v_cvt_pk_bf16_f32 v52, v72, v73
	v_cvt_pk_bf16_f32 v53, v74, v75
	v_cvt_pk_bf16_f32 v54, v76, v77
	v_cvt_pk_bf16_f32 v55, v78, v79
	v_cvt_pk_bf16_f32 v56, v159, v160
	v_cvt_pk_bf16_f32 v57, v82, v83
	v_cvt_pk_bf16_f32 v58, v84, v85
	v_cvt_pk_bf16_f32 v59, v86, v87
	v_cvt_pk_bf16_f32 v60, v88, v89
	v_cvt_pk_bf16_f32 v61, v90, v91
	v_cvt_pk_bf16_f32 v62, v92, v93
	v_cvt_pk_bf16_f32 v63, v94, v95
	v_cvt_pk_bf16_f32 v64, v96, v97
	v_cvt_pk_bf16_f32 v65, v98, v99
	v_cvt_pk_bf16_f32 v66, v100, v101
	v_cvt_pk_bf16_f32 v67, v102, v103
	v_cvt_pk_bf16_f32 v68, v104, v105
	v_cvt_pk_bf16_f32 v69, v106, v107
	v_cvt_pk_bf16_f32 v70, v108, v109
	v_cvt_pk_bf16_f32 v71, v110, v111
	v_cvt_pk_bf16_f32 v72, v112, v113
	v_cvt_pk_bf16_f32 v73, v114, v115
	v_cvt_pk_bf16_f32 v74, v116, v117
	v_cvt_pk_bf16_f32 v75, v118, v119
	v_cvt_pk_bf16_f32 v76, v120, v121
	v_cvt_pk_bf16_f32 v77, v122, v123
	v_cvt_pk_bf16_f32 v78, v124, v125
	v_cvt_pk_bf16_f32 v79, v126, v127
	s_waitcnt vmcnt(0) lgkmcnt(0)
	v_lshl_add_u64 v[0:1], v[188:189], 0, s[0:1]
	v_lshl_add_u64 v[2:3], v[190:191], 0, s[0:1]
	v_lshl_add_u64 v[4:5], v[192:193], 0, s[0:1]
	v_lshl_add_u64 v[6:7], v[194:195], 0, s[0:1]
	s_mov_b64 s[0:1], 0
	s_waitcnt lgkmcnt(0)
	s_barrier
.LBB0_434:
	v_lshl_add_u64 v[8:9], v[6:7], 0, s[0:1]
	s_mov_b32 m0, s24
	s_nop 0
	global_load_lds_dwordx4 v[8:9], off
	v_lshl_add_u64 v[8:9], v[4:5], 0, s[0:1]
	s_add_i32 m0, s24, 0x400
	s_nop 0
	global_load_lds_dwordx4 v[8:9], off
	v_lshl_add_u64 v[8:9], v[2:3], 0, s[0:1]
	s_add_i32 m0, s24, 0x800
	s_nop 0
	global_load_lds_dwordx4 v[8:9], off
	v_lshl_add_u64 v[8:9], v[0:1], 0, s[0:1]
	s_add_i32 m0, s24, 0xc00
	s_add_u32 s0, s0, 0x100000
	global_load_lds_dwordx4 v[8:9], off
	s_addc_u32 s1, s1, 0
	s_addk_i32 s24, 0x1000
	s_cmp_eq_u32 s0, 0x400000
	s_cbranch_scc0 .LBB0_434
	v_add_f32_e32 v0, v80, v81
	v_rcp_f32_e32 v82, v0
	s_waitcnt vmcnt(0) lgkmcnt(0)
	v_lshl_add_u64 v[0:1], v[200:201], 1, s[10:11]
	v_lshl_add_u64 v[0:1], s[12:13], 1, v[0:1]
	v_mov_b32_e32 v199, v209
	v_lshl_add_u64 v[80:81], v[0:1], 0, v[198:199]
	s_mov_b32 s0, 0
	s_waitcnt vmcnt(0) lgkmcnt(0)
	s_barrier
	v_readfirstlane_b32 s98, v202
	s_nop 3
	s_bitcmp1_b32 s98, 8
	s_cbranch_scc0 .Lxa_stag2
	s_sleep 4
.Lxa_stag2:
.LBB0_436:
	v_add_u32_e32 v83, s0, v250
	ds_read_b64_tr_b16 v[0:1], v83
	ds_read_b64_tr_b16 v[2:3], v83 offset:512
	ds_read_b64_tr_b16 v[84:85], v83 offset:1024
	ds_read_b64_tr_b16 v[86:87], v83 offset:1536
	s_addk_i32 s0, 0x4000
	s_cmp_lg_u32 s0, 0x20000
	s_waitcnt lgkmcnt(2)
	v_mfma_f32_32x32x16_bf16 v[0:15], v[0:3], v[16:19], 0
	s_waitcnt lgkmcnt(0)
	v_mfma_f32_32x32x16_bf16 v[0:15], v[84:87], v[20:23], v[0:15]
	ds_read_b64_tr_b16 v[84:85], v83 offset:2048
	ds_read_b64_tr_b16 v[86:87], v83 offset:2560
	s_waitcnt lgkmcnt(0)
	v_mfma_f32_32x32x16_bf16 v[0:15], v[84:87], v[24:27], v[0:15]
	ds_read_b64_tr_b16 v[84:85], v83 offset:3072
	ds_read_b64_tr_b16 v[86:87], v83 offset:3584
	s_waitcnt lgkmcnt(0)
	v_mfma_f32_32x32x16_bf16 v[0:15], v[84:87], v[28:31], v[0:15]
	ds_read_b64_tr_b16 v[84:85], v83 offset:4096
	ds_read_b64_tr_b16 v[86:87], v83 offset:4608
	s_waitcnt lgkmcnt(0)
	v_mfma_f32_32x32x16_bf16 v[0:15], v[84:87], v[32:35], v[0:15]
	ds_read_b64_tr_b16 v[84:85], v83 offset:5120
	ds_read_b64_tr_b16 v[86:87], v83 offset:5632
	s_waitcnt lgkmcnt(0)
	v_mfma_f32_32x32x16_bf16 v[0:15], v[84:87], v[36:39], v[0:15]
	ds_read_b64_tr_b16 v[84:85], v83 offset:6144
	ds_read_b64_tr_b16 v[86:87], v83 offset:6656
	s_waitcnt lgkmcnt(0)
	v_mfma_f32_32x32x16_bf16 v[0:15], v[84:87], v[40:43], v[0:15]
	ds_read_b64_tr_b16 v[84:85], v83 offset:7168
	ds_read_b64_tr_b16 v[86:87], v83 offset:7680
	s_waitcnt lgkmcnt(0)
	v_mfma_f32_32x32x16_bf16 v[0:15], v[84:87], v[44:47], v[0:15]
	ds_read_b64_tr_b16 v[84:85], v83 offset:8192
	ds_read_b64_tr_b16 v[86:87], v83 offset:8704
	s_waitcnt lgkmcnt(0)
	v_mfma_f32_32x32x16_bf16 v[0:15], v[84:87], v[48:51], v[0:15]
	ds_read_b64_tr_b16 v[84:85], v83 offset:9216
	ds_read_b64_tr_b16 v[86:87], v83 offset:9728
	s_waitcnt lgkmcnt(0)
	v_mfma_f32_32x32x16_bf16 v[0:15], v[84:87], v[52:55], v[0:15]
	ds_read_b64_tr_b16 v[84:85], v83 offset:10240
	ds_read_b64_tr_b16 v[86:87], v83 offset:10752
	s_waitcnt lgkmcnt(0)
	v_mfma_f32_32x32x16_bf16 v[0:15], v[84:87], v[56:59], v[0:15]
	ds_read_b64_tr_b16 v[84:85], v83 offset:11264
	ds_read_b64_tr_b16 v[86:87], v83 offset:11776
	s_waitcnt lgkmcnt(0)
	v_mfma_f32_32x32x16_bf16 v[0:15], v[84:87], v[60:63], v[0:15]
	ds_read_b64_tr_b16 v[84:85], v83 offset:12288
	ds_read_b64_tr_b16 v[86:87], v83 offset:12800
	s_waitcnt lgkmcnt(0)
	v_mfma_f32_32x32x16_bf16 v[0:15], v[84:87], v[64:67], v[0:15]
	ds_read_b64_tr_b16 v[84:85], v83 offset:13312
	ds_read_b64_tr_b16 v[86:87], v83 offset:13824
	s_waitcnt lgkmcnt(0)
	v_mfma_f32_32x32x16_bf16 v[0:15], v[84:87], v[68:71], v[0:15]
	ds_read_b64_tr_b16 v[84:85], v83 offset:14336
	ds_read_b64_tr_b16 v[86:87], v83 offset:14848
	s_waitcnt lgkmcnt(0)
	v_mfma_f32_32x32x16_bf16 v[0:15], v[84:87], v[72:75], v[0:15]
	ds_read_b64_tr_b16 v[84:85], v83 offset:15360
	ds_read_b64_tr_b16 v[86:87], v83 offset:15872
	s_waitcnt lgkmcnt(0)
	v_mfma_f32_32x32x16_bf16 v[0:15], v[84:87], v[76:79], v[0:15]
	s_nop 11
	v_mul_f32_e32 v0, v82, v0
	v_mul_f32_e32 v1, v82, v1
	v_cvt_pk_bf16_f32 v0, v0, v1
	v_mul_f32_e32 v1, v82, v2
	v_mul_f32_e32 v2, v82, v3
	v_cvt_pk_bf16_f32 v1, v1, v2
	v_mul_f32_e32 v2, v82, v4
	v_mul_f32_e32 v3, v82, v5
	v_cvt_pk_bf16_f32 v2, v2, v3
	v_mul_f32_e32 v3, v82, v6
	v_mul_f32_e32 v4, v82, v7
	v_cvt_pk_bf16_f32 v3, v3, v4
	v_mul_f32_e32 v4, v82, v8
	v_mul_f32_e32 v5, v82, v9
	v_cvt_pk_bf16_f32 v4, v4, v5
	v_mul_f32_e32 v5, v82, v10
	v_mul_f32_e32 v6, v82, v11
	v_cvt_pk_bf16_f32 v5, v5, v6
	v_mul_f32_e32 v6, v82, v12
	v_mul_f32_e32 v7, v82, v13
	v_cvt_pk_bf16_f32 v6, v6, v7
	v_mul_f32_e32 v7, v82, v14
	v_mul_f32_e32 v8, v82, v15
	v_cvt_pk_bf16_f32 v7, v7, v8
	v_permlane32_swap_b32_e32 v0, v2
	v_permlane32_swap_b32_e32 v1, v3
	v_permlane32_swap_b32_e32 v4, v6
	v_permlane32_swap_b32_e32 v5, v7
	global_store_dwordx4 v[80:81], v[0:3], off
	global_store_dwordx4 v[80:81], v[4:7], off offset:32
	v_lshl_add_u64 v[80:81], v[80:81], 0, 64
	s_cbranch_scc1 .LBB0_436
	s_waitcnt vmcnt(0) lgkmcnt(0)
	s_add_i32 s16, s16, 1
	s_mov_b64 s[0:1], 0
	s_barrier
	s_branch .LBB0_427

; #define LAS __attribute__((address_space(3)))
; __device__ __forceinline__ void glds16(const void* gsrc, LAS unsigned char* dst_uniform) { __builtin_amdgcn_global_load_lds((const unsigned*)gsrc, (LAS unsigned*)dst_uniform, 16, 0, 0); }
; #define ATT_SYNC() do { asm volatile("s_waitcnt vmcnt(0) lgkmcnt(0)" ::: "memory"); __syncthreads(); } while (0)
; __device__ __forceinline__ void dil_unit(LAS unsigned char* lds, const LAS float* btab, const bf16_t* QKV, int gi, int ldil, int b, int h, int r, int ub, bf16_t* AO, float* lseacc, const int tid) {
;     ...
;     for (int t = 0; t < 5; ++t) { f32x16 acc = {}; const lds_cptr kp = (lds_cptr)lds + (32 * wid + 32 * t + r32) * 256;
; #pragma unroll
;         for (int s = 0; s < 8; ++s) { const bf16x8 kf = *(const LAS bf16x8*)(kp + (((2 * s + hi) ^ r15) << 4)); acc = __builtin_amdgcn_mfma_f32_32x32x16_bf16(kf, qf[s], acc, 0, 0, 0); }
;         S[t] = acc; }
;     ATT_SYNC();
; #pragma unroll 1
;     for (int ii = 0; ii < 12; ++ii) { const int i = wid * 12 + ii, d0 = i / 24, ks = i % 24, kk = 16 * ks + 8 * hi + ((lane >> 2) & 7), cc = lane & 3; int ki = k0 + kk; ki = ki < 0 ? 0 : (ki >= sub_len ? sub_len - 1 : ki);
;         glds16(base + (tokb + ((size_t)ki << ldil)) * 3072 + 2048 + 32 * d0 + 8 * cc, lds + i * 1024); }
;     float m = -3.0e38f;
; #pragma unroll
;     for (int t = 0; t < 5; ++t)
; #pragma unroll
;         for (int rr = 0; rr < 16; ++rr) { const int cr = (rr & 3) + 8 * (rr >> 2) + 4 * hi, jk = 32 * t + cr - r32, ki = k0 + 32 * wid + 32 * t + cr;
;             float s = S[t][rr] + btab[jk + 32];
;             s = ((unsigned)ki < (unsigned)sub_len) ? s : -1e30f;
;             S[t][rr] = s; m = fmaxf(m, s); }
.LBB0_665:
	s_mul_i32 s30, s20, 12
	s_add_i32 s30, s30, s29
	s_mul_hi_i32 s31, s30, 0x2aaaaaab
	s_lshr_b32 s35, s31, 31
	s_ashr_i32 s31, s31, 2
	s_add_i32 s35, s31, s35
	s_mul_i32 s31, s35, 24
	s_sub_i32 s30, s30, s31
	v_lshl_add_u32 v65, s30, 4, v64
	v_min_i32_e32 v66, s18, v65
	v_cmp_lt_i32_e32 vcc, -1, v65
	v_mov_b64_e32 v[68:69], s[2:3]
	v_lshlrev_b32_e32 v208, 1, v212
	v_cndmask_b32_e32 v66, 0, v66, vcc
	v_ashrrev_i32_e32 v67, 31, v66
	v_lshlrev_b64 v[66:67], s12, v[66:67]
	v_lshl_add_u64 v[66:67], v[66:67], 0, s[0:1]
	v_mad_u64_u32 v[68:69], s[30:31], v66, s36, v[68:69]
	v_mov_b32_e32 v66, v69
	v_mad_u64_u32 v[66:67], s[30:31], v67, s36, v[66:67]
	s_lshl_b32 s30, s35, 5
	v_mov_b32_e32 v69, v66
	s_ashr_i32 s31, s30, 31
	v_lshl_add_u64 v[66:67], s[30:31], 1, v[68:69]
	v_lshl_add_u64 v[66:67], v[66:67], 0, v[208:209]
	s_mov_b64 s[30:31], 0x1000
	v_lshl_add_u64 v[66:67], v[66:67], 0, s[30:31]
	s_mov_b32 m0, s26
	s_add_i32 s29, s29, 1
	global_load_lds_dwordx4 v[66:67], off
	s_addk_i32 s26, 0x400
	s_cmp_eq_u32 s29, 12
	s_cbranch_scc0 .LBB0_665
	v_readfirstlane_b32 s98, v237
	s_nop 3
	s_bitcmp1_b32 s98, 8
	s_cbranch_scc0 .Ldil_stag1
	s_sleep 10
.Ldil_stag1:
	v_mfma_f32_32x32x16_bf16 v[64:79], v[48:51], v[0:3], 0
	s_add_i32 s0, 0, 0x20000
	s_add_i32 s1, s28, s27
	s_mov_b32 s2, 0xff61b1e6
	s_lshl_b32 s96, s24, 1
	v_mfma_f32_32x32x16_bf16 v[64:79], v[24:27], v[80:83], v[64:79]
	v_mfma_f32_32x32x16_bf16 v[64:79], v[52:55], v[84:87], v[64:79]
	v_mfma_f32_32x32x16_bf16 v[64:79], v[32:35], v[88:91], v[64:79]
	v_mfma_f32_32x32x16_bf16 v[64:79], v[56:59], v[92:95], v[64:79]
	v_mfma_f32_32x32x16_bf16 v[64:79], v[36:39], v[96:99], v[64:79]
	v_mfma_f32_32x32x16_bf16 v[64:79], v[60:63], v[100:103], v[64:79]
	v_mfma_f32_32x32x16_bf16 v[48:63], v[44:47], v[0:3], 0
	v_mfma_f32_32x32x16_bf16 v[48:63], v[4:7], v[80:83], v[48:63]
	v_mfma_f32_32x32x16_bf16 v[48:63], v[128:131], v[84:87], v[48:63]
	v_mfma_f32_32x32x16_bf16 v[48:63], v[8:11], v[88:91], v[48:63]
	v_mfma_f32_32x32x16_bf16 v[48:63], v[136:139], v[92:95], v[48:63]
	v_mfma_f32_32x32x16_bf16 v[64:79], v[40:43], v[104:107], v[64:79]
	v_mfma_f32_32x32x16_bf16 v[48:63], v[12:15], v[96:99], v[48:63]
	v_mfma_f32_32x32x16_bf16 v[32:47], v[20:23], v[0:3], 0
	v_mfma_f32_32x32x16_bf16 v[48:63], v[144:147], v[100:103], v[48:63]
	v_mfma_f32_32x32x16_bf16 v[32:47], v[148:151], v[80:83], v[32:47]
	v_mfma_f32_32x32x16_bf16 v[48:63], v[16:19], v[104:107], v[48:63]
	v_mfma_f32_32x32x16_bf16 v[32:47], v[28:31], v[84:87], v[32:47]
	v_mfma_f32_32x32x16_bf16 v[16:31], v[192:195], v[0:3], 0
	v_mfma_f32_32x32x16_bf16 v[0:15], v[140:143], v[0:3], 0
	v_mfma_f32_32x32x16_bf16 v[16:31], v[116:119], v[80:83], v[16:31]
	v_mfma_f32_32x32x16_bf16 v[0:15], v[152:155], v[80:83], v[0:15]
	v_lshlrev_b32_e32 v80, 2, v240
	v_add_u32_e32 v83, s0, v220
	v_lshlrev_b32_e32 v82, 2, v239
	v_mfma_f32_32x32x16_bf16 v[16:31], v[196:199], v[84:87], v[16:31]
	v_mfma_f32_32x32x16_bf16 v[0:15], v[156:159], v[84:87], v[0:15]
	v_or_b32_e32 v84, s1, v82
	v_or_b32_e32 v85, 1, v82
	v_cmp_gt_u32_e32 vcc, s17, v84
	v_or_b32_e32 v86, 2, v82
	v_or_b32_e32 v87, s1, v86
	v_mfma_f32_32x32x16_bf16 v[32:47], v[160:163], v[88:91], v[32:47]
	v_mfma_f32_32x32x16_bf16 v[16:31], v[120:123], v[88:91], v[16:31]
	v_mfma_f32_32x32x16_bf16 v[0:15], v[164:167], v[88:91], v[0:15]
	v_or_b32_e32 v91, 8, v82
	v_or_b32_e32 v90, 16, v82
	v_mfma_f32_32x32x16_bf16 v[32:47], v[108:111], v[92:95], v[32:47]
	v_mfma_f32_32x32x16_bf16 v[16:31], v[200:203], v[92:95], v[16:31]
	v_mfma_f32_32x32x16_bf16 v[0:15], v[172:175], v[92:95], v[0:15]
	v_or_b32_e32 v92, 10, v82
	v_mfma_f32_32x32x16_bf16 v[32:47], v[168:171], v[96:99], v[32:47]
	v_mfma_f32_32x32x16_bf16 v[16:31], v[124:127], v[96:99], v[16:31]
	v_mfma_f32_32x32x16_bf16 v[0:15], v[180:183], v[96:99], v[0:15]
	v_sub_u32_e32 v98, v83, v80
	ds_read2_b32 v[80:81], v98 offset0:32 offset1:33
	ds_read2_b32 v[94:95], v98 offset0:50 offset1:51
	s_waitcnt lgkmcnt(0)
	v_add_f32_e32 v64, v64, v80
	v_or_b32_e32 v80, s1, v85
	v_cndmask_b32_e32 v64, v231, v64, vcc
	v_add_f32_e32 v65, v65, v81
	v_cmp_gt_u32_e32 vcc, s17, v80
	ds_read2_b32 v[80:81], v98 offset0:34 offset1:35
	v_add_f32_e32 v74, v74, v94
	v_cndmask_b32_e32 v65, v231, v65, vcc
	v_cmp_gt_u32_e32 vcc, s17, v87
	v_or_b32_e32 v87, 3, v82
	s_waitcnt lgkmcnt(0)
	v_add_f32_e32 v66, v66, v80
	v_or_b32_e32 v80, s1, v87
	v_cndmask_b32_e32 v66, v231, v66, vcc
	v_add_f32_e32 v67, v67, v81
	v_cmp_gt_u32_e32 vcc, s17, v80
	ds_read2_b32 v[80:81], v98 offset0:40 offset1:41
	v_max3_f32 v84, v64, s2, v65
	v_cndmask_b32_e32 v67, v231, v67, vcc
	v_max3_f32 v88, v84, v66, v67
	v_or_b32_e32 v84, s1, v91
	v_cmp_gt_u32_e32 vcc, s17, v84
	v_or_b32_e32 v84, 9, v82
	s_waitcnt lgkmcnt(0)
	v_add_f32_e32 v68, v68, v80
	v_or_b32_e32 v80, s1, v84
	v_cndmask_b32_e32 v68, v231, v68, vcc
	v_add_f32_e32 v69, v69, v81
	v_cmp_gt_u32_e32 vcc, s17, v80
	v_or_b32_e32 v81, s1, v92
	v_add_f32_e32 v75, v75, v95
	v_cndmask_b32_e32 v69, v231, v69, vcc
	v_max3_f32 v80, v88, v68, v69
	ds_read2_b32 v[88:89], v98 offset0:42 offset1:43
	v_cmp_gt_u32_e32 vcc, s17, v81
	v_or_b32_e32 v81, 11, v82
	v_or_b32_e32 v94, 24, v82
	v_or_b32_e32 v95, 25, v82
	s_waitcnt lgkmcnt(0)
	v_add_f32_e32 v70, v70, v88
	v_or_b32_e32 v88, s1, v81
	v_cndmask_b32_e32 v70, v231, v70, vcc
	v_add_f32_e32 v71, v71, v89
	v_cmp_gt_u32_e32 vcc, s17, v88
	ds_read2_b32 v[88:89], v98 offset0:48 offset1:49
	v_mfma_f32_32x32x16_bf16 v[32:47], v[112:115], v[100:103], v[32:47]
	v_cndmask_b32_e32 v71, v231, v71, vcc
	v_max3_f32 v93, v80, v70, v71
	v_or_b32_e32 v80, s1, v90
	s_waitcnt lgkmcnt(0)
; __device__ __forceinline__ float shx(float v, int lane, int mask) { return __builtin_bit_cast(float, __builtin_amdgcn_ds_bpermute((lane ^ mask) << 2, __builtin_bit_cast(int, v))); }
; __device__ __forceinline__ void dil_unit(LAS unsigned char* lds, const LAS float* btab, const bf16_t* QKV, int gi, int ldil, int b, int h, int r, int ub, bf16_t* AO, float* lseacc, const int tid) {
;     ...
;         for (int rr = 0; rr < 16; ++rr) { const int cr = (rr & 3) + 8 * (rr >> 2) + 4 * hi, jk = 32 * t + cr - r32, ki = k0 + 32 * wid + 32 * t + cr;
;             float s = S[t][rr] + btab[jk + 32];
;             s = ((unsigned)ki < (unsigned)sub_len) ? s : -1e30f;
;             S[t][rr] = s; m = fmaxf(m, s); }
;     m = fmaxf(m, pg8::shx(m, lane, 32));
	v_add_f32_e32 v72, v72, v88
	v_cmp_gt_u32_e32 vcc, s17, v80
	v_or_b32_e32 v88, 17, v82
	v_add_f32_e32 v73, v73, v89
	v_cndmask_b32_e32 v80, v231, v72, vcc
	v_or_b32_e32 v72, s1, v88
	v_cmp_gt_u32_e32 vcc, s17, v72
	v_or_b32_e32 v89, 18, v82
	v_mfma_f32_32x32x16_bf16 v[16:31], v[204:207], v[100:103], v[16:31]
	v_cndmask_b32_e32 v72, v231, v73, vcc
	v_max3_f32 v96, v93, v80, v72
	v_or_b32_e32 v73, s1, v89
	v_or_b32_e32 v93, 19, v82
	v_cmp_gt_u32_e32 vcc, s17, v73
	v_or_b32_e32 v73, s1, v93
	s_add_i32 s2, s1, 32
	v_cndmask_b32_e32 v74, v231, v74, vcc
	v_cmp_gt_u32_e32 vcc, s17, v73
	v_mfma_f32_32x32x16_bf16 v[0:15], v[184:187], v[100:103], v[0:15]
	s_nop 0
	v_cndmask_b32_e32 v73, v231, v75, vcc
	v_max3_f32 v99, v96, v74, v73
	ds_read2_b32 v[96:97], v98 offset0:56 offset1:57
	v_or_b32_e32 v75, s1, v94
	v_cmp_gt_u32_e32 vcc, s17, v75
	v_or_b32_e32 v75, s1, v95
	v_mfma_f32_32x32x16_bf16 v[32:47], v[176:179], v[104:107], v[32:47]
	s_waitcnt lgkmcnt(0)
	v_add_f32_e32 v76, v76, v96
	v_cndmask_b32_e32 v76, v231, v76, vcc
	v_add_f32_e32 v77, v77, v97
	v_cmp_gt_u32_e32 vcc, s17, v75
	v_or_b32_e32 v96, 26, v82
	v_or_b32_e32 v97, 27, v82
	v_cndmask_b32_e32 v75, v231, v77, vcc
	v_max3_f32 v100, v99, v76, v75
	ds_read2_b32 v[98:99], v98 offset0:58 offset1:59
	v_or_b32_e32 v77, s1, v96
	v_cmp_gt_u32_e32 vcc, s17, v77
	v_mfma_f32_32x32x16_bf16 v[16:31], v[132:135], v[104:107], v[16:31]
	s_waitcnt lgkmcnt(0)
	v_add_f32_e32 v78, v78, v98
	v_sub_u32_e32 v98, 32, v240
	v_lshlrev_b32_e32 v101, 2, v98
	v_add_u32_e32 v98, v83, v101
	v_add_f32_e32 v79, v79, v99
	ds_read2_b32 v[98:99], v98 offset0:32 offset1:33
	v_cndmask_b32_e32 v77, v231, v78, vcc
	v_or_b32_e32 v78, s1, v97
	v_cmp_gt_u32_e32 vcc, s17, v78
	v_add3_u32 v102, s0, v101, v220
	s_waitcnt lgkmcnt(0)
	v_add_f32_e32 v48, v48, v98
	v_cndmask_b32_e32 v78, v231, v79, vcc
	v_max3_f32 v79, v100, v77, v78
	v_or_b32_e32 v100, s2, v82
	v_cmp_gt_u32_e32 vcc, s17, v100
	v_or_b32_e32 v98, s2, v85
	v_add_f32_e32 v49, v49, v99
	v_cndmask_b32_e32 v48, v231, v48, vcc
	v_cmp_gt_u32_e32 vcc, s17, v98
	ds_read2_b32 v[98:99], v102 offset0:34 offset1:35
	v_mfma_f32_32x32x16_bf16 v[0:15], v[188:191], v[104:107], v[0:15]
	v_cndmask_b32_e32 v49, v231, v49, vcc
	v_max3_f32 v100, v79, v48, v49
	v_or_b32_e32 v79, s2, v86
	s_waitcnt lgkmcnt(0)
	v_add_f32_e32 v50, v50, v98
	v_add_f32_e32 v51, v51, v99
	ds_read2_b32 v[98:99], v102 offset0:40 offset1:41
	v_cmp_gt_u32_e32 vcc, s17, v79
	s_waitcnt lgkmcnt(0)
	v_add_f32_e32 v52, v52, v98
	v_cndmask_b32_e32 v79, v231, v50, vcc
	v_or_b32_e32 v50, s2, v87
	v_cmp_gt_u32_e32 vcc, s17, v50
	v_add_f32_e32 v53, v53, v99
	ds_read2_b32 v[98:99], v102 offset0:42 offset1:43
	v_cndmask_b32_e32 v50, v231, v51, vcc
	v_or_b32_e32 v51, s2, v91
	v_cmp_gt_u32_e32 vcc, s17, v51
	v_or_b32_e32 v51, s2, v84
	v_max3_f32 v100, v100, v79, v50
	v_cndmask_b32_e32 v52, v231, v52, vcc
	v_cmp_gt_u32_e32 vcc, s17, v51
	s_nop 1
	v_cndmask_b32_e32 v51, v231, v53, vcc
	v_max3_f32 v53, v100, v52, v51
	v_or_b32_e32 v100, s2, v92
	v_cmp_gt_u32_e32 vcc, s17, v100
	ds_read2_b32 v[100:101], v102 offset0:48 offset1:49
	s_waitcnt lgkmcnt(0)
	v_add_f32_e32 v54, v54, v98
	v_cndmask_b32_e32 v98, v231, v54, vcc
	v_or_b32_e32 v54, s2, v81
	v_cmp_gt_u32_e32 vcc, s17, v54
	v_add_f32_e32 v54, v56, v100
	v_add_f32_e32 v56, v57, v101
	ds_read2_b32 v[100:101], v102 offset0:50 offset1:51
	v_add_f32_e32 v55, v55, v99
	v_cndmask_b32_e32 v55, v231, v55, vcc
	v_max3_f32 v99, v53, v98, v55
	v_or_b32_e32 v53, s2, v90
	v_cmp_gt_u32_e32 vcc, s17, v53
	v_or_b32_e32 v53, s2, v88
	s_waitcnt lgkmcnt(0)
	v_add_f32_e32 v57, v58, v100
	v_cndmask_b32_e32 v54, v231, v54, vcc
	v_cmp_gt_u32_e32 vcc, s17, v53
	v_add_f32_e32 v58, v59, v101
	ds_read2_b32 v[100:101], v102 offset0:56 offset1:57
	v_cndmask_b32_e32 v53, v231, v56, vcc
	v_or_b32_e32 v56, s2, v89
	v_cmp_gt_u32_e32 vcc, s17, v56
	v_or_b32_e32 v56, s2, v93
	s_waitcnt lgkmcnt(0)
	v_add_f32_e32 v59, v60, v100
	v_cndmask_b32_e32 v57, v231, v57, vcc
	v_cmp_gt_u32_e32 vcc, s17, v56
	v_add_f32_e32 v60, v61, v101
	v_or_b32_e32 v100, s2, v96
	v_cndmask_b32_e32 v56, v231, v58, vcc
	v_or_b32_e32 v58, s2, v94
	v_cmp_gt_u32_e32 vcc, s17, v58
	v_or_b32_e32 v58, s2, v95
	v_max3_f32 v99, v99, v54, v53
	v_cndmask_b32_e32 v59, v231, v59, vcc
	v_cmp_gt_u32_e32 vcc, s17, v58
	v_max3_f32 v99, v99, v57, v56
	s_nop 0
	v_cndmask_b32_e32 v58, v231, v60, vcc
	ds_read2_b32 v[60:61], v102 offset0:58 offset1:59
	v_cmp_gt_u32_e32 vcc, s17, v100
	v_or_b32_e32 v100, s25, v82
	v_max3_f32 v99, v99, v59, v58
	s_waitcnt lgkmcnt(0)
	v_add_f32_e32 v60, v62, v60
	v_or_b32_e32 v62, s2, v97
	v_cndmask_b32_e32 v60, v231, v60, vcc
	v_cmp_gt_u32_e32 vcc, s17, v62
	v_sub_u32_e32 v62, 64, v240
	v_lshlrev_b32_e32 v101, 2, v62
	v_add_u32_e32 v62, v83, v101
	v_add_f32_e32 v61, v63, v61
	ds_read2_b32 v[62:63], v62 offset0:32 offset1:33
	v_cndmask_b32_e32 v61, v231, v61, vcc
	v_cmp_gt_u32_e32 vcc, s17, v100
	v_add3_u32 v102, s0, v101, v220
	v_or_b32_e32 v100, s25, v86
	s_waitcnt lgkmcnt(0)
	v_add_f32_e32 v32, v32, v62
	v_or_b32_e32 v62, s25, v85
	v_cndmask_b32_e32 v32, v231, v32, vcc
	v_add_f32_e32 v33, v33, v63
	v_cmp_gt_u32_e32 vcc, s17, v62
	ds_read2_b32 v[62:63], v102 offset0:34 offset1:35
	v_max3_f32 v99, v99, v60, v61
	v_cndmask_b32_e32 v33, v231, v33, vcc
	v_cmp_gt_u32_e32 vcc, s17, v100
	ds_read2_b32 v[100:101], v102 offset0:40 offset1:41
	s_waitcnt lgkmcnt(0)
	v_add_f32_e32 v34, v34, v62
	v_cndmask_b32_e32 v62, v231, v34, vcc
	v_or_b32_e32 v34, s25, v87
	v_add_f32_e32 v35, v35, v63
	v_add_f32_e32 v36, v36, v100
	v_add_f32_e32 v37, v37, v101
	ds_read2_b32 v[100:101], v102 offset0:42 offset1:43
	v_cmp_gt_u32_e32 vcc, s17, v34
	v_max3_f32 v99, v99, v32, v33
	s_add_i32 s2, s1, 0x60
	v_cndmask_b32_e32 v34, v231, v35, vcc
	v_or_b32_e32 v35, s25, v91
	v_cmp_gt_u32_e32 vcc, s17, v35
	v_or_b32_e32 v35, s25, v84
	s_waitcnt lgkmcnt(0)
; __device__ __forceinline__ float shx(float v, int lane, int mask) { return __builtin_bit_cast(float, __builtin_amdgcn_ds_bpermute((lane ^ mask) << 2, __builtin_bit_cast(int, v))); }
; __device__ __forceinline__ void dil_unit(LAS unsigned char* lds, const LAS float* btab, const bf16_t* QKV, int gi, int ldil, int b, int h, int r, int ub, bf16_t* AO, float* lseacc, const int tid) {
;     ...
;         for (int rr = 0; rr < 16; ++rr) { const int cr = (rr & 3) + 8 * (rr >> 2) + 4 * hi, jk = 32 * t + cr - r32, ki = k0 + 32 * wid + 32 * t + cr;
;             float s = S[t][rr] + btab[jk + 32];
;             s = ((unsigned)ki < (unsigned)sub_len) ? s : -1e30f;
;             S[t][rr] = s; m = fmaxf(m, s); }
;     m = fmaxf(m, pg8::shx(m, lane, 32));
	v_add_f32_e32 v38, v38, v100
	v_cndmask_b32_e32 v36, v231, v36, vcc
	v_cmp_gt_u32_e32 vcc, s17, v35
	v_add_f32_e32 v39, v39, v101
	ds_read2_b32 v[100:101], v102 offset0:48 offset1:49
	v_max3_f32 v63, v99, v62, v34
	v_cndmask_b32_e32 v35, v231, v37, vcc
	v_max3_f32 v37, v63, v36, v35
	v_or_b32_e32 v63, s25, v92
	v_cmp_gt_u32_e32 vcc, s17, v63
	s_addk_i32 s1, 0x80
	s_nop 0
	v_cndmask_b32_e32 v63, v231, v38, vcc
	v_or_b32_e32 v38, s25, v81
	v_cmp_gt_u32_e32 vcc, s17, v38
	s_waitcnt lgkmcnt(0)
	v_add_f32_e32 v38, v40, v100
	v_add_f32_e32 v40, v41, v101
	ds_read2_b32 v[100:101], v102 offset0:50 offset1:51
	v_cndmask_b32_e32 v39, v231, v39, vcc
	v_max3_f32 v99, v37, v63, v39
	v_or_b32_e32 v37, s25, v90
	v_cmp_gt_u32_e32 vcc, s17, v37
	s_waitcnt lgkmcnt(0)
	v_add_f32_e32 v41, v42, v100
	v_add_f32_e32 v42, v43, v101
	ds_read2_b32 v[100:101], v102 offset0:56 offset1:57
	v_or_b32_e32 v37, s25, v88
	v_cndmask_b32_e32 v38, v231, v38, vcc
	v_cmp_gt_u32_e32 vcc, s17, v37
	s_waitcnt lgkmcnt(0)
	v_add_f32_e32 v43, v44, v100
	v_cndmask_b32_e32 v37, v231, v40, vcc
	v_or_b32_e32 v40, s25, v89
	v_cmp_gt_u32_e32 vcc, s17, v40
	v_or_b32_e32 v40, s25, v93
	v_add_f32_e32 v44, v45, v101
	v_cndmask_b32_e32 v41, v231, v41, vcc
	v_cmp_gt_u32_e32 vcc, s17, v40
	ds_read2_b32 v[100:101], v102 offset0:58 offset1:59
	v_max3_f32 v99, v99, v38, v37
	v_cndmask_b32_e32 v40, v231, v42, vcc
	v_or_b32_e32 v42, s25, v94
	v_cmp_gt_u32_e32 vcc, s17, v42
	v_or_b32_e32 v42, s25, v95
	s_waitcnt lgkmcnt(0)
	v_add_f32_e32 v45, v46, v100
	v_cndmask_b32_e32 v43, v231, v43, vcc
	v_cmp_gt_u32_e32 vcc, s17, v42
	v_add_f32_e32 v46, v47, v101
	v_or_b32_e32 v100, s2, v82
	v_cndmask_b32_e32 v42, v231, v44, vcc
	v_or_b32_e32 v44, s25, v96
	v_cmp_gt_u32_e32 vcc, s17, v44
	v_or_b32_e32 v44, s25, v97
	v_max3_f32 v99, v99, v41, v40
	v_cndmask_b32_e32 v45, v231, v45, vcc
	v_cmp_gt_u32_e32 vcc, s17, v44
	v_max3_f32 v99, v99, v43, v42
	v_or_b32_e32 v82, s1, v82
	v_cndmask_b32_e32 v44, v231, v46, vcc
	v_sub_u32_e32 v46, 0x60, v240
	v_lshlrev_b32_e32 v101, 2, v46
	v_add_u32_e32 v46, v83, v101
	ds_read2_b32 v[46:47], v46 offset0:32 offset1:33
	v_cmp_gt_u32_e32 vcc, s17, v100
	v_add3_u32 v102, s0, v101, v220
	v_or_b32_e32 v100, s2, v86
	v_max3_f32 v99, v99, v45, v44
	s_waitcnt lgkmcnt(0)
	v_add_f32_e32 v16, v16, v46
	v_or_b32_e32 v46, s2, v85
	v_cndmask_b32_e32 v16, v231, v16, vcc
	v_add_f32_e32 v17, v17, v47
	v_cmp_gt_u32_e32 vcc, s17, v46
	ds_read2_b32 v[46:47], v102 offset0:34 offset1:35
	s_nop 0
	v_cndmask_b32_e32 v17, v231, v17, vcc
	v_cmp_gt_u32_e32 vcc, s17, v100
	ds_read2_b32 v[100:101], v102 offset0:40 offset1:41
	s_waitcnt lgkmcnt(0)
	v_add_f32_e32 v18, v18, v46
	v_cndmask_b32_e32 v46, v231, v18, vcc
	v_or_b32_e32 v18, s2, v87
	v_add_f32_e32 v19, v19, v47
	v_add_f32_e32 v20, v20, v100
	v_add_f32_e32 v21, v21, v101
	ds_read2_b32 v[100:101], v102 offset0:42 offset1:43
	v_cmp_gt_u32_e32 vcc, s17, v18
	v_max3_f32 v99, v99, v16, v17
	s_waitcnt lgkmcnt(0)
	v_add_f32_e32 v22, v22, v100
	v_cndmask_b32_e32 v18, v231, v19, vcc
	v_or_b32_e32 v19, s2, v91
	v_cmp_gt_u32_e32 vcc, s17, v19
	v_or_b32_e32 v19, s2, v84
	v_add_f32_e32 v23, v23, v101
	v_cndmask_b32_e32 v20, v231, v20, vcc
	v_cmp_gt_u32_e32 vcc, s17, v19
	ds_read2_b32 v[100:101], v102 offset0:48 offset1:49
	v_max3_f32 v47, v99, v46, v18
	v_cndmask_b32_e32 v19, v231, v21, vcc
	v_max3_f32 v21, v47, v20, v19
	v_or_b32_e32 v47, s2, v92
	v_cmp_gt_u32_e32 vcc, s17, v47
	s_nop 1
	v_cndmask_b32_e32 v47, v231, v22, vcc
	v_or_b32_e32 v22, s2, v81
	v_cmp_gt_u32_e32 vcc, s17, v22
	s_waitcnt lgkmcnt(0)
	v_add_f32_e32 v22, v24, v100
	v_add_f32_e32 v24, v25, v101
	ds_read2_b32 v[100:101], v102 offset0:50 offset1:51
	v_cndmask_b32_e32 v23, v231, v23, vcc
	v_max3_f32 v99, v21, v47, v23
	v_or_b32_e32 v21, s2, v90
	v_cmp_gt_u32_e32 vcc, s17, v21
	s_waitcnt lgkmcnt(0)
	v_add_f32_e32 v25, v26, v100
	v_add_f32_e32 v26, v27, v101
	ds_read2_b32 v[100:101], v102 offset0:56 offset1:57
	v_or_b32_e32 v21, s2, v88
	v_cndmask_b32_e32 v22, v231, v22, vcc
	v_cmp_gt_u32_e32 vcc, s17, v21
	s_waitcnt lgkmcnt(0)
	v_add_f32_e32 v27, v28, v100
	v_cndmask_b32_e32 v21, v231, v24, vcc
	v_or_b32_e32 v24, s2, v89
	v_cmp_gt_u32_e32 vcc, s17, v24
	v_or_b32_e32 v24, s2, v93
	v_add_f32_e32 v28, v29, v101
	v_cndmask_b32_e32 v25, v231, v25, vcc
	v_cmp_gt_u32_e32 vcc, s17, v24
	ds_read2_b32 v[100:101], v102 offset0:58 offset1:59
	v_max3_f32 v99, v99, v22, v21
	v_cndmask_b32_e32 v24, v231, v26, vcc
	v_or_b32_e32 v26, s2, v94
	v_cmp_gt_u32_e32 vcc, s17, v26
	v_or_b32_e32 v26, s2, v95
	s_waitcnt lgkmcnt(0)
	v_add_f32_e32 v29, v30, v100
	v_cndmask_b32_e32 v27, v231, v27, vcc
	v_cmp_gt_u32_e32 vcc, s17, v26
	v_add_f32_e32 v30, v31, v101
	v_max3_f32 v99, v99, v25, v24
	v_cndmask_b32_e32 v26, v231, v28, vcc
	v_or_b32_e32 v28, s2, v96
	v_cmp_gt_u32_e32 vcc, s17, v28
	v_or_b32_e32 v28, s2, v97
	v_max3_f32 v99, v99, v27, v26
	v_cndmask_b32_e32 v29, v231, v29, vcc
	v_cmp_gt_u32_e32 vcc, s17, v28
	s_nop 1
	v_cndmask_b32_e32 v28, v231, v30, vcc
	v_sub_u32_e32 v30, 0x80, v240
	v_lshlrev_b32_e32 v100, 2, v30
	v_add_u32_e32 v30, v83, v100
	ds_read2_b32 v[30:31], v30 offset0:32 offset1:33
	v_cmp_gt_u32_e32 vcc, s17, v82
	v_add3_u32 v100, s0, v100, v220
	v_or_b32_e32 v83, s1, v86
	v_max3_f32 v99, v99, v29, v28
	s_waitcnt lgkmcnt(0)
	v_add_f32_e32 v0, v0, v30
	v_or_b32_e32 v30, s1, v85
	v_cndmask_b32_e32 v0, v231, v0, vcc
	v_add_f32_e32 v1, v1, v31
	v_cmp_gt_u32_e32 vcc, s17, v30
	ds_read2_b32 v[30:31], v100 offset0:34 offset1:35
	s_waitcnt lgkmcnt(0)
; __device__ __forceinline__ float shx(float v, int lane, int mask) { return __builtin_bit_cast(float, __builtin_amdgcn_ds_bpermute((lane ^ mask) << 2, __builtin_bit_cast(int, v))); }
; __device__ __forceinline__ void dil_unit(LAS unsigned char* lds, const LAS float* btab, const bf16_t* QKV, int gi, int ldil, int b, int h, int r, int ub, bf16_t* AO, float* lseacc, const int tid) {
;     ...
;         for (int rr = 0; rr < 16; ++rr) { const int cr = (rr & 3) + 8 * (rr >> 2) + 4 * hi, jk = 32 * t + cr - r32, ki = k0 + 32 * wid + 32 * t + cr;
;             float s = S[t][rr] + btab[jk + 32];
;             s = ((unsigned)ki < (unsigned)sub_len) ? s : -1e30f;
;             S[t][rr] = s; m = fmaxf(m, s); }
;     m = fmaxf(m, pg8::shx(m, lane, 32));
;     float l = 0.f;
; #pragma unroll
;     for (int t = 0; t < 5; ++t)
; #pragma unroll
;         for (int rr = 0; rr < 16; ++rr) { const float p = __builtin_amdgcn_exp2f(S[t][rr] - m); S[t][rr] = p; l += p; }
;     l += pg8::shx(l, lane, 32);
	v_add_f32_e32 v2, v2, v30
	v_cndmask_b32_e32 v1, v231, v1, vcc
	v_cmp_gt_u32_e32 vcc, s17, v83
	v_add_f32_e32 v3, v3, v31
	v_max3_f32 v82, v99, v0, v1
	v_cndmask_b32_e32 v30, v231, v2, vcc
	v_or_b32_e32 v2, s1, v87
	v_cmp_gt_u32_e32 vcc, s17, v2
	s_nop 1
	v_cndmask_b32_e32 v2, v231, v3, vcc
	v_max3_f32 v31, v82, v30, v2
	ds_read2_b32 v[82:83], v100 offset0:40 offset1:41
	v_or_b32_e32 v3, s1, v91
	v_cmp_gt_u32_e32 vcc, s17, v3
	v_or_b32_e32 v3, s1, v84
	ds_read2_b32 v[84:85], v100 offset0:48 offset1:49
	s_waitcnt lgkmcnt(0)
	v_add_f32_e32 v4, v4, v82
	v_add_f32_e32 v5, v5, v83
	ds_read2_b32 v[82:83], v100 offset0:42 offset1:43
	v_cndmask_b32_e32 v4, v231, v4, vcc
	v_cmp_gt_u32_e32 vcc, s17, v3
	s_waitcnt lgkmcnt(0)
	v_add_f32_e32 v6, v6, v82
	v_cndmask_b32_e32 v3, v231, v5, vcc
	v_max3_f32 v5, v31, v4, v3
	v_or_b32_e32 v31, s1, v92
	v_cmp_gt_u32_e32 vcc, s17, v31
	v_add_f32_e32 v7, v7, v83
	s_nop 0
	v_cndmask_b32_e32 v82, v231, v6, vcc
	v_or_b32_e32 v6, s1, v81
	v_cmp_gt_u32_e32 vcc, s17, v6
	v_or_b32_e32 v6, s1, v90
	v_or_b32_e32 v81, s1, v96
	v_cndmask_b32_e32 v31, v231, v7, vcc
	v_add_f32_e32 v7, v8, v84
	v_add_f32_e32 v8, v9, v85
	ds_read2_b32 v[84:85], v100 offset0:50 offset1:51
	v_cmp_gt_u32_e32 vcc, s17, v6
	v_or_b32_e32 v6, s1, v88
	v_max3_f32 v5, v5, v82, v31
	v_cndmask_b32_e32 v7, v231, v7, vcc
	v_cmp_gt_u32_e32 vcc, s17, v6
	s_waitcnt lgkmcnt(0)
	v_add_f32_e32 v9, v10, v84
	v_add_f32_e32 v10, v11, v85
	ds_read2_b32 v[84:85], v100 offset0:56 offset1:57
	v_cndmask_b32_e32 v6, v231, v8, vcc
	v_or_b32_e32 v8, s1, v89
	v_cmp_gt_u32_e32 vcc, s17, v8
	v_or_b32_e32 v8, s1, v93
	s_waitcnt lgkmcnt(0)
	v_add_f32_e32 v11, v12, v84
	v_cndmask_b32_e32 v9, v231, v9, vcc
	v_cmp_gt_u32_e32 vcc, s17, v8
	v_add_f32_e32 v12, v13, v85
	v_max3_f32 v5, v5, v7, v6
	v_cndmask_b32_e32 v8, v231, v10, vcc
	v_or_b32_e32 v10, s1, v94
	v_cmp_gt_u32_e32 vcc, s17, v10
	v_or_b32_e32 v10, s1, v95
	v_max3_f32 v5, v5, v9, v8
	v_cndmask_b32_e32 v11, v231, v11, vcc
	v_cmp_gt_u32_e32 vcc, s17, v10
	s_nop 1
	v_cndmask_b32_e32 v10, v231, v12, vcc
	ds_read2_b32 v[12:13], v100 offset0:58 offset1:59
	v_cmp_gt_u32_e32 vcc, s17, v81
	v_max3_f32 v5, v5, v11, v10
	s_waitcnt lgkmcnt(0)
	v_add_f32_e32 v12, v14, v12
	v_cndmask_b32_e32 v81, v231, v12, vcc
	v_or_b32_e32 v12, s1, v97
	v_add_f32_e32 v13, v15, v13
	v_cmp_gt_u32_e32 vcc, s17, v12
	v_lshlrev_b32_e32 v12, 2, v238
	v_xor_b32_e32 v12, 0x80, v12
	v_cndmask_b32_e32 v15, v231, v13, vcc
	v_max3_f32 v5, v5, v81, v15
	ds_bpermute_b32 v13, v12, v5
	s_and_b64 vcc, exec, s[10:11]
	s_waitcnt lgkmcnt(0)
	v_max_f32_e32 v13, v13, v13
	v_max_f32_e32 v5, v5, v13
	v_sub_f32_e32 v13, v64, v5
	v_exp_f32_e32 v13, v13
	v_sub_f32_e32 v14, v65, v5
	v_exp_f32_e32 v14, v14
	v_sub_f32_e32 v73, v73, v5
	v_add_f32_e32 v64, 0, v13
	v_exp_f32_e32 v73, v73
	v_add_f32_e32 v65, v14, v64
	v_sub_f32_e32 v64, v66, v5
	v_exp_f32_e32 v64, v64
	v_sub_f32_e32 v75, v75, v5
	v_exp_f32_e32 v75, v75
	v_sub_f32_e32 v48, v48, v5
	v_add_f32_e32 v66, v64, v65
	v_sub_f32_e32 v65, v67, v5
	v_exp_f32_e32 v65, v65
	v_exp_f32_e32 v48, v48
	v_sub_f32_e32 v49, v49, v5
	v_exp_f32_e32 v49, v49
	v_add_f32_e32 v67, v65, v66
	v_sub_f32_e32 v66, v68, v5
	v_exp_f32_e32 v66, v66
	v_sub_f32_e32 v50, v50, v5
	v_exp_f32_e32 v50, v50
	v_sub_f32_e32 v52, v52, v5
	v_add_f32_e32 v68, v66, v67
	v_sub_f32_e32 v67, v69, v5
	v_exp_f32_e32 v67, v67
	v_sub_f32_e32 v51, v51, v5
	v_exp_f32_e32 v51, v51
	v_sub_f32_e32 v55, v55, v5
	v_add_f32_e32 v69, v67, v68
	v_sub_f32_e32 v68, v70, v5
	v_exp_f32_e32 v68, v68
	v_exp_f32_e32 v55, v55
	v_sub_f32_e32 v54, v54, v5
	v_exp_f32_e32 v83, v54
	v_add_f32_e32 v70, v68, v69
	v_sub_f32_e32 v69, v71, v5
	v_exp_f32_e32 v69, v69
	v_sub_f32_e32 v53, v53, v5
	v_exp_f32_e32 v84, v53
	v_sub_f32_e32 v53, v57, v5
	v_add_f32_e32 v71, v69, v70
	v_sub_f32_e32 v70, v80, v5
	v_exp_f32_e32 v70, v70
	v_exp_f32_e32 v85, v53
	v_sub_f32_e32 v53, v56, v5
	v_exp_f32_e32 v86, v53
	v_add_f32_e32 v80, v70, v71
	v_sub_f32_e32 v71, v72, v5
	v_exp_f32_e32 v71, v71
	v_sub_f32_e32 v72, v74, v5
	v_exp_f32_e32 v72, v72
	v_sub_f32_e32 v53, v59, v5
	v_add_f32_e32 v80, v71, v80
	v_exp_f32_e32 v87, v53
	v_add_f32_e32 v74, v72, v80
	v_add_f32_e32 v80, v73, v74
	v_sub_f32_e32 v74, v76, v5
	v_exp_f32_e32 v74, v74
	v_sub_f32_e32 v53, v58, v5
	v_exp_f32_e32 v88, v53
	v_sub_f32_e32 v53, v60, v5
	v_add_f32_e32 v76, v74, v80
	v_add_f32_e32 v80, v75, v76
	v_sub_f32_e32 v76, v77, v5
	v_exp_f32_e32 v76, v76
	v_sub_f32_e32 v77, v78, v5
	v_exp_f32_e32 v77, v77
	v_exp_f32_e32 v89, v53
	v_add_f32_e32 v80, v76, v80
	v_sub_f32_e32 v53, v61, v5
	v_add_f32_e32 v78, v77, v80
	v_add_f32_e32 v78, v48, v78
	v_add_f32_e32 v80, v49, v78
	v_sub_f32_e32 v78, v79, v5
	v_exp_f32_e32 v78, v78
	v_exp_f32_e32 v90, v53
	v_sub_f32_e32 v32, v32, v5
	v_exp_f32_e32 v32, v32
	v_add_f32_e32 v79, v78, v80
	v_add_f32_e32 v80, v50, v79
	v_exp_f32_e32 v79, v52
	v_sub_f32_e32 v33, v33, v5
	v_exp_f32_e32 v33, v33
	v_sub_f32_e32 v53, v62, v5
	v_add_f32_e32 v52, v79, v80
	v_sub_f32_e32 v80, v98, v5
	v_exp_f32_e32 v80, v80
	v_add_f32_e32 v52, v51, v52
	v_exp_f32_e32 v91, v53
	v_sub_f32_e32 v34, v34, v5
	v_add_f32_e32 v52, v80, v52
	v_add_f32_e32 v52, v55, v52
	v_add_f32_e32 v52, v83, v52
	v_add_f32_e32 v52, v84, v52
	v_add_f32_e32 v52, v85, v52
	v_add_f32_e32 v52, v86, v52
	v_add_f32_e32 v52, v87, v52
	v_add_f32_e32 v52, v88, v52
	v_add_f32_e32 v52, v89, v52
	v_add_f32_e32 v52, v90, v52
	v_exp_f32_e32 v34, v34
	v_sub_f32_e32 v36, v36, v5
	v_add_f32_e32 v52, v32, v52
	v_exp_f32_e32 v36, v36
	v_sub_f32_e32 v35, v35, v5
	v_add_f32_e32 v52, v33, v52
	v_exp_f32_e32 v35, v35
	v_sub_f32_e32 v53, v63, v5
	v_add_f32_e32 v52, v91, v52
; __device__ __forceinline__ float shx(float v, int lane, int mask) { return __builtin_bit_cast(float, __builtin_amdgcn_ds_bpermute((lane ^ mask) << 2, __builtin_bit_cast(int, v))); }
; __device__ __forceinline__ void dil_unit(LAS unsigned char* lds, const LAS float* btab, const bf16_t* QKV, int gi, int ldil, int b, int h, int r, int ub, bf16_t* AO, float* lseacc, const int tid) {
;     ...
;         for (int rr = 0; rr < 16; ++rr) { const float p = __builtin_amdgcn_exp2f(S[t][rr] - m); S[t][rr] = p; l += p; }
;     l += pg8::shx(l, lane, 32);
;     const float inv = __builtin_amdgcn_rcpf(l), lse = m + __builtin_amdgcn_logf(l);
;     bf16x8 pf[10];
; #pragma unroll
;     for (int t = 0; t < 5; ++t) { pf[2 * t] = pack8(S[t], 0); pf[2 * t + 1] = pack8(S[t], 8); }
;     bf16_t* orow = AO + qtok * 1024 + h * 128;
;     u32x4 oldv[4][2] = {};
;     if (gi > 0) {
; #pragma unroll
;         for (int d0 = 0; d0 < 4; ++d0)
; #pragma unroll
;             for (int g2 = 0; g2 < 2; ++g2) oldv[d0][g2] = *(const u32x4*)(orow + 32 * d0 + 16 * g2 + (hi ? 8 : 0)); }
	v_exp_f32_e32 v92, v53
	v_sub_f32_e32 v39, v39, v5
	v_add_f32_e32 v52, v34, v52
	v_exp_f32_e32 v39, v39
	v_sub_f32_e32 v38, v38, v5
	v_add_f32_e32 v52, v36, v52
	v_exp_f32_e32 v38, v38
	v_sub_f32_e32 v37, v37, v5
	v_add_f32_e32 v52, v35, v52
	v_exp_f32_e32 v37, v37
	v_sub_f32_e32 v41, v41, v5
	v_add_f32_e32 v52, v92, v52
	v_exp_f32_e32 v41, v41
	v_sub_f32_e32 v40, v40, v5
	v_add_f32_e32 v52, v39, v52
	v_exp_f32_e32 v93, v40
	v_sub_f32_e32 v43, v43, v5
	v_add_f32_e32 v52, v38, v52
	v_exp_f32_e32 v43, v43
	v_sub_f32_e32 v42, v42, v5
	v_add_f32_e32 v52, v37, v52
	v_exp_f32_e32 v42, v42
	v_sub_f32_e32 v45, v45, v5
	v_add_f32_e32 v52, v41, v52
	v_exp_f32_e32 v94, v45
	v_sub_f32_e32 v44, v44, v5
	v_add_f32_e32 v40, v93, v52
	v_exp_f32_e32 v95, v44
	v_sub_f32_e32 v16, v16, v5
	v_add_f32_e32 v40, v43, v40
	v_exp_f32_e32 v16, v16
	v_sub_f32_e32 v17, v17, v5
	v_add_f32_e32 v40, v42, v40
	v_exp_f32_e32 v17, v17
	v_sub_f32_e32 v44, v46, v5
	v_add_f32_e32 v40, v94, v40
	v_exp_f32_e32 v96, v44
	v_sub_f32_e32 v18, v18, v5
	v_add_f32_e32 v40, v95, v40
	v_exp_f32_e32 v18, v18
	v_sub_f32_e32 v20, v20, v5
	v_add_f32_e32 v40, v16, v40
	v_exp_f32_e32 v20, v20
	v_sub_f32_e32 v19, v19, v5
	v_add_f32_e32 v40, v17, v40
	v_exp_f32_e32 v19, v19
	v_sub_f32_e32 v44, v47, v5
	v_add_f32_e32 v40, v96, v40
	v_exp_f32_e32 v97, v44
	v_sub_f32_e32 v23, v23, v5
	v_add_f32_e32 v40, v18, v40
	v_exp_f32_e32 v23, v23
	v_sub_f32_e32 v22, v22, v5
	v_add_f32_e32 v40, v20, v40
	v_exp_f32_e32 v22, v22
	v_sub_f32_e32 v21, v21, v5
	v_add_f32_e32 v40, v19, v40
	v_exp_f32_e32 v21, v21
	v_sub_f32_e32 v25, v25, v5
	v_add_f32_e32 v40, v97, v40
	v_exp_f32_e32 v25, v25
	v_sub_f32_e32 v24, v24, v5
	v_add_f32_e32 v40, v23, v40
	v_exp_f32_e32 v24, v24
	v_sub_f32_e32 v27, v27, v5
	v_add_f32_e32 v40, v22, v40
	v_exp_f32_e32 v27, v27
	v_sub_f32_e32 v26, v26, v5
	v_add_f32_e32 v40, v21, v40
	v_exp_f32_e32 v26, v26
	v_sub_f32_e32 v29, v29, v5
	v_add_f32_e32 v40, v25, v40
	v_exp_f32_e32 v29, v29
	v_sub_f32_e32 v28, v28, v5
	v_add_f32_e32 v40, v24, v40
	v_exp_f32_e32 v28, v28
	v_sub_f32_e32 v0, v0, v5
	v_add_f32_e32 v40, v27, v40
	v_exp_f32_e32 v0, v0
	v_sub_f32_e32 v1, v1, v5
	v_add_f32_e32 v40, v26, v40
	v_exp_f32_e32 v1, v1
	v_sub_f32_e32 v30, v30, v5
	v_add_f32_e32 v40, v29, v40
	v_exp_f32_e32 v30, v30
	v_sub_f32_e32 v2, v2, v5
	v_add_f32_e32 v40, v28, v40
	v_exp_f32_e32 v98, v2
	v_sub_f32_e32 v4, v4, v5
	v_add_f32_e32 v40, v0, v40
	v_exp_f32_e32 v4, v4
	v_sub_f32_e32 v3, v3, v5
	v_add_f32_e32 v40, v1, v40
	v_exp_f32_e32 v99, v3
	v_sub_f32_e32 v3, v82, v5
	v_add_f32_e32 v40, v30, v40
	v_exp_f32_e32 v82, v3
	v_sub_f32_e32 v3, v31, v5
	v_add_f32_e32 v2, v98, v40
	v_exp_f32_e32 v31, v3
	v_sub_f32_e32 v3, v7, v5
	v_add_f32_e32 v2, v4, v2
	v_exp_f32_e32 v7, v3
	v_sub_f32_e32 v3, v6, v5
	v_add_f32_e32 v2, v99, v2
	v_exp_f32_e32 v6, v3
	v_sub_f32_e32 v3, v9, v5
	v_add_f32_e32 v2, v82, v2
	v_exp_f32_e32 v9, v3
	v_sub_f32_e32 v3, v8, v5
	v_add_f32_e32 v2, v31, v2
	v_exp_f32_e32 v8, v3
	v_sub_f32_e32 v3, v11, v5
	v_add_f32_e32 v2, v7, v2
	v_exp_f32_e32 v11, v3
	v_sub_f32_e32 v3, v10, v5
	v_add_f32_e32 v2, v6, v2
	v_exp_f32_e32 v10, v3
	v_sub_f32_e32 v3, v81, v5
	v_add_f32_e32 v2, v9, v2
	v_exp_f32_e32 v81, v3
	v_sub_f32_e32 v3, v15, v5
	v_add_f32_e32 v2, v8, v2
	v_exp_f32_e32 v15, v3
	v_add_f32_e32 v2, v11, v2
	v_add_f32_e32 v2, v10, v2
	v_add_f32_e32 v2, v81, v2
	v_add_f32_e32 v2, v15, v2
	ds_bpermute_b32 v3, v12, v2
	v_cvt_pk_bf16_f32 v60, v13, v14
	v_cvt_pk_bf16_f32 v61, v64, v65
	v_cvt_pk_bf16_f32 v62, v66, v67
	v_cvt_pk_bf16_f32 v63, v68, v69
	v_cvt_pk_bf16_f32 v56, v70, v71
	v_cvt_pk_bf16_f32 v57, v72, v73
	v_cvt_pk_bf16_f32 v58, v74, v75
	v_cvt_pk_bf16_f32 v59, v76, v77
	v_cvt_pk_bf16_f32 v52, v48, v49
	v_cvt_pk_bf16_f32 v53, v78, v50
	v_cvt_pk_bf16_f32 v54, v79, v51
	v_cvt_pk_bf16_f32 v55, v80, v55
	v_cvt_pk_bf16_f32 v48, v83, v84
	v_cvt_pk_bf16_f32 v49, v85, v86
	v_cvt_pk_bf16_f32 v50, v87, v88
	v_cvt_pk_bf16_f32 v51, v89, v90
	v_cvt_pk_bf16_f32 v44, v32, v33
	v_cvt_pk_bf16_f32 v45, v91, v34
	v_cvt_pk_bf16_f32 v46, v36, v35
	v_cvt_pk_bf16_f32 v47, v92, v39
	v_cvt_pk_bf16_f32 v40, v38, v37
	v_cvt_pk_bf16_f32 v41, v41, v93
	v_cvt_pk_bf16_f32 v42, v43, v42
	v_cvt_pk_bf16_f32 v43, v94, v95
	v_cvt_pk_bf16_f32 v36, v16, v17
	v_cvt_pk_bf16_f32 v37, v96, v18
	v_cvt_pk_bf16_f32 v38, v20, v19
	v_cvt_pk_bf16_f32 v39, v97, v23
	v_cvt_pk_bf16_f32 v32, v22, v21
	v_cvt_pk_bf16_f32 v33, v25, v24
	v_cvt_pk_bf16_f32 v34, v27, v26
	v_cvt_pk_bf16_f32 v35, v29, v28
	v_cvt_pk_bf16_f32 v28, v0, v1
	v_lshlrev_b64 v[0:1], 11, v[218:219]
	v_lshl_add_u64 v[0:1], s[6:7], 0, v[0:1]
	v_cvt_pk_bf16_f32 v29, v30, v98
	v_cvt_pk_bf16_f32 v30, v4, v99
	v_cvt_pk_bf16_f32 v31, v82, v31
	v_cvt_pk_bf16_f32 v24, v7, v6
	v_cvt_pk_bf16_f32 v25, v9, v8
	v_cvt_pk_bf16_f32 v26, v11, v10
	v_cvt_pk_bf16_f32 v27, v81, v15
	v_lshl_add_u64 v[0:1], v[0:1], 0, s[96:97]
	v_mov_b32_e32 v88, 0
	v_mov_b32_e32 v16, 0
	v_mov_b32_e32 v17, 0
	v_mov_b32_e32 v18, 0
	v_mov_b32_e32 v19, 0
	v_mov_b32_e32 v20, 0
	v_mov_b32_e32 v21, 0
	v_mov_b32_e32 v22, 0
	v_mov_b32_e32 v23, 0
	v_mov_b32_e32 v64, 0
	v_mov_b32_e32 v65, 0
	v_mov_b32_e32 v66, 0
	v_mov_b32_e32 v67, 0
	v_mov_b32_e32 v68, 0
	v_mov_b32_e32 v69, 0
	v_mov_b32_e32 v70, 0
	v_mov_b32_e32 v71, 0
	v_mov_b32_e32 v72, 0
	v_mov_b32_e32 v73, 0
	v_mov_b32_e32 v74, 0
	v_mov_b32_e32 v75, 0
	v_mov_b32_e32 v76, 0
	v_mov_b32_e32 v77, 0
	v_mov_b32_e32 v78, 0
	v_mov_b32_e32 v79, 0
	v_mov_b32_e32 v80, 0
	v_mov_b32_e32 v81, 0
	v_mov_b32_e32 v82, 0
	v_mov_b32_e32 v83, 0
	v_mov_b32_e32 v84, 0
	v_mov_b32_e32 v85, 0
	v_mov_b32_e32 v86, 0
	v_mov_b32_e32 v87, 0
	s_cbranch_vccz .LBB0_668
	v_and_b32_e32 v4, 8, v221
	v_lshlrev_b32_e32 v208, 1, v4
	v_lshl_add_u64 v[6:7], v[0:1], 0, v[208:209]
	global_load_dwordx4 v[84:87], v[6:7], off
	global_load_dwordx4 v[80:83], v[6:7], off offset:32
	global_load_dwordx4 v[76:79], v[6:7], off offset:64
	global_load_dwordx4 v[72:75], v[6:7], off offset:96
	global_load_dwordx4 v[68:71], v[6:7], off offset:128
	global_load_dwordx4 v[64:67], v[6:7], off offset:160
	global_load_dwordx4 v[20:23], v[6:7], off offset:192
	global_load_dwordx4 v[16:19], v[6:7], off offset:224

; __device__ __forceinline__ v4i16_t vtr(lds_cptr p) { return __builtin_amdgcn_ds_read_tr16_b64_v4i16((LAS v4i16_t*)p); }
; __device__ __forceinline__ unsigned pkbf(float lo, float hi) { return pg8::cvt_pk_bf16(lo, hi); }
; #define ATT_MRG(N, O) pkbf(__uint_as_float((O) << 16) * wa + __uint_as_float((N) << 16) * wb, __uint_as_float((O) & 0xffff0000u) * wa + __uint_as_float((N) & 0xffff0000u) * wb)
; template <bool MERGE> __device__ __forceinline__ void store_ot(const f32x16& acc, float sc, bf16_t* rowp  , int hi, float wa, float wb, const u32x4 (&oldv)[2]) {
;     ...
;     for (int g = 0; g < 4; ++g) { w[2 * g] = pkbf(acc[4 * g] * sc, acc[4 * g + 1] * sc); w[2 * g + 1] = pkbf(acc[4 * g + 2] * sc, acc[4 * g + 3] * sc); }
; #pragma unroll
;     for (int g = 0; g < 4; g += 2) {
;         const auto rx = __builtin_amdgcn_permlane32_swap(w[2 * g], w[2 * g + 2], false, false);
;         const auto ry = __builtin_amdgcn_permlane32_swap(w[2 * g + 1], w[2 * g + 3], false, false);
;         u32x4 o; o.x = rx[0]; o.y = ry[0]; o.z = rx[1]; o.w = ry[1];
;         u32x4* dst = (u32x4*)(rowp + 8 * g + (hi ? 8 : 0));
;         if (MERGE) { const u32x4 old = oldv[g >> 1];
;     ...
;             o.x = ATT_MRG(o.x, old.x); o.y = ATT_MRG(o.y, old.y); o.z = ATT_MRG(o.z, old.z); o.w = ATT_MRG(o.w, old.w);
;     ...
;         }
;         *dst = o;
; __device__ __forceinline__ void dil_unit(LAS unsigned char* lds, const LAS float* btab, const bf16_t* QKV, int gi, int ldil, int b, int h, int r, int ub, bf16_t* AO, float* lseacc, const int tid) {
;     ...
;     const lds_cptr vb = (lds_cptr)lds + ((lane >> 4) & 1) * 32 + (lane & 3) * 8 + (4 * hi + ((lane & 15) >> 2)) * 64 + 2 * wid * 1024;
; #pragma unroll
;     for (int d0 = 0; d0 < 4; ++d0) { f32x16 acc = {};
; #pragma unroll
;         for (int k = 0; k < 10; ++k) { const v4i16_t lo = vtr(vb + (d0 * 24 + k) * 1024), hh = vtr(vb + (d0 * 24 + k) * 1024 + 512);
;             const bf16x8 vf = {lo[0], lo[1], lo[2], lo[3], hh[0], hh[1], hh[2], hh[3]};
;             acc = __builtin_amdgcn_mfma_f32_32x32x16_bf16(vf, pf[k], acc, 0, 0, 0); }
;         if (gi > 0) store_ot<true>(acc, inv, orow + 32 * d0, hi, wa, wb, oldv[d0]); else store_ot<false>(acc, inv, orow + 32 * d0, hi, 0.f, 0.f, oldv[d0]); }
.LBB0_671:
	v_rcp_f32_e32 v95, v2
	v_lshlrev_b32_e32 v2, 1, v237
	v_and_b32_e32 v2, 32, v2
	v_add_u32_e32 v2, 0, v2
	v_lshlrev_b32_e32 v3, 8, v239
	v_lshlrev_b32_e32 v4, 4, v237
	v_and_b32_e32 v4, 0xc0, v4
	v_add3_u32 v2, v2, v212, v3
	s_lshl_b32 s0, s20, 11
	v_cmp_gt_u32_e64 s[36:37], 32, v238
	v_add3_u32 v96, v2, v4, s0
	s_waitcnt vmcnt(0) lgkmcnt(0)
	s_waitcnt vmcnt(0)
	v_cndmask_b32_e64 v208, 16, 0, s[36:37]
	s_barrier
	v_readfirstlane_b32 s98, v237
	s_nop 3
	s_bitcmp1_b32 s98, 8
	s_cbranch_scc0 .Ldil_stag2
	s_sleep 3
.Ldil_stag2:
	v_lshl_add_u64 v[92:93], v[0:1], 0, v[208:209]
	ds_read_b64_tr_b16 v[0:1], v96
	ds_read_b64_tr_b16 v[2:3], v96 offset:512
	s_waitcnt lgkmcnt(0)
	v_mfma_f32_32x32x16_bf16 v[0:15], v[0:3], v[60:63], 0
	ds_read_b64_tr_b16 v[98:99], v96 offset:1024
	ds_read_b64_tr_b16 v[100:101], v96 offset:1536
	s_mov_b64 s[0:1], -1
	s_and_b64 vcc, exec, s[40:41]
	s_waitcnt lgkmcnt(0)
	v_mfma_f32_32x32x16_bf16 v[0:15], v[98:101], v[56:59], v[0:15]
	ds_read_b64_tr_b16 v[98:99], v96 offset:2048
	ds_read_b64_tr_b16 v[100:101], v96 offset:2560
	s_waitcnt lgkmcnt(0)
	v_mfma_f32_32x32x16_bf16 v[0:15], v[98:101], v[52:55], v[0:15]
	ds_read_b64_tr_b16 v[98:99], v96 offset:3072
	ds_read_b64_tr_b16 v[100:101], v96 offset:3584
	s_waitcnt lgkmcnt(0)
	v_mfma_f32_32x32x16_bf16 v[0:15], v[98:101], v[48:51], v[0:15]
	ds_read_b64_tr_b16 v[98:99], v96 offset:4096
	ds_read_b64_tr_b16 v[100:101], v96 offset:4608
	s_waitcnt lgkmcnt(0)
	v_mfma_f32_32x32x16_bf16 v[0:15], v[98:101], v[44:47], v[0:15]
	ds_read_b64_tr_b16 v[98:99], v96 offset:5120
	ds_read_b64_tr_b16 v[100:101], v96 offset:5632
	s_waitcnt lgkmcnt(0)
	v_mfma_f32_32x32x16_bf16 v[0:15], v[98:101], v[40:43], v[0:15]
	ds_read_b64_tr_b16 v[98:99], v96 offset:6144
	ds_read_b64_tr_b16 v[100:101], v96 offset:6656
	s_waitcnt lgkmcnt(0)
	v_mfma_f32_32x32x16_bf16 v[0:15], v[98:101], v[36:39], v[0:15]
	ds_read_b64_tr_b16 v[98:99], v96 offset:7168
	ds_read_b64_tr_b16 v[100:101], v96 offset:7680
	s_waitcnt lgkmcnt(0)
	v_mfma_f32_32x32x16_bf16 v[0:15], v[98:101], v[32:35], v[0:15]
	ds_read_b64_tr_b16 v[98:99], v96 offset:8192
	ds_read_b64_tr_b16 v[100:101], v96 offset:8704
	s_waitcnt lgkmcnt(0)
	v_mfma_f32_32x32x16_bf16 v[0:15], v[98:101], v[28:31], v[0:15]
	ds_read_b64_tr_b16 v[98:99], v96 offset:9216
	ds_read_b64_tr_b16 v[100:101], v96 offset:9728
	s_waitcnt lgkmcnt(0)
	v_mfma_f32_32x32x16_bf16 v[0:15], v[98:101], v[24:27], v[0:15]
	s_nop 11
	v_mul_f32_e32 v104, v95, v0
	v_mul_f32_e32 v106, v95, v1
	v_mul_f32_e32 v102, v95, v2
	v_mul_f32_e32 v105, v95, v3
	v_mul_f32_e32 v100, v95, v4
	v_mul_f32_e32 v103, v95, v5
	v_mul_f32_e32 v98, v95, v6
	v_mul_f32_e32 v101, v95, v7
	v_mul_f32_e32 v97, v95, v8
	v_mul_f32_e32 v99, v95, v9
	v_mul_f32_e32 v7, v95, v10
	v_mul_f32_e32 v9, v95, v11
	v_mul_f32_e32 v5, v95, v12
	v_mul_f32_e32 v8, v95, v13
	v_mul_f32_e32 v4, v95, v14
	v_mul_f32_e32 v6, v95, v15
	s_cbranch_vccz .LBB0_673
	v_cvt_pk_bf16_f32 v10, v104, v106
	v_cvt_pk_bf16_f32 v11, v102, v105
	v_cvt_pk_bf16_f32 v12, v100, v103
	v_cvt_pk_bf16_f32 v13, v98, v101
	v_cvt_pk_bf16_f32 v0, v97, v99
	v_cvt_pk_bf16_f32 v1, v7, v9
	v_cvt_pk_bf16_f32 v2, v5, v8
	v_cvt_pk_bf16_f32 v3, v4, v6
	s_nop 0
	v_permlane32_swap_b32_e32 v10, v12
	v_permlane32_swap_b32_e32 v11, v13
	global_store_dwordx4 v[92:93], v[10:13], off
	v_permlane32_swap_b32_e32 v0, v2
	v_permlane32_swap_b32_e32 v1, v3
	s_mov_b64 s[0:1], 0
